# stacked: early LDS waits in the diff-attention loop plus LDS fragment reads used as the M0-to-DMA separator in the GEMM load segments
# speedup vs baseline: 1.0029x; 1.0017x over previous
; #define PG8_STAGE(bufoff, gbase, voff) do { _Pragma("unroll") for (int _i = 0; _i < 2; ++_i) \
;         __builtin_amdgcn_global_load_lds((const unsigned*)((const char*)(gbase) + (voff)[_i]), (PG8_LAS unsigned*)(lds + (bufoff) + ldsw + _i * 8192), 16, 0, 0); } while (0)
; #define PG8_LDA(dst, b, h) do { _Pragma("unroll") for (int m = 0; m < 4; ++m) _Pragma("unroll") for (int k = 0; k < 2; ++k) dst[m][k] = *(const PG8_LAS bf16x8*)(lds + PG8_SA(b, h) + aoff + m * 2048 + k * 1024); } while (0)
; #define PG8_LDB(dst, b, h) do { _Pragma("unroll") for (int n = 0; n < 2; ++n) _Pragma("unroll") for (int k = 0; k < 2; ++k) dst[n][k] = *(const PG8_LAS bf16x8*)(lds + PG8_SB(b, h) + boff + n * 2048 + k * 1024); } while (0)
; #define PG8_MMA(ai, bj, At, Bt) do { __builtin_amdgcn_s_setprio(1); _Pragma("unroll") for (int m = 0; m < 4; ++m) _Pragma("unroll") for (int n = 0; n < 2; ++n) _Pragma("unroll") for (int k = 0; k < 2; ++k) \
;         acc[ai][bj][m][n] = __builtin_amdgcn_mfma_f32_16x16x32_bf16(Bt[n][k], At[m][k], acc[ai][bj][m][n], 0, 0, 0); __builtin_amdgcn_s_setprio(0); } while (0)
; #define PG8_WAIT_V(n) asm volatile("s_waitcnt vmcnt(" #n ")" ::: "memory")
; #define PG8_WAIT_L(n) asm volatile("s_waitcnt lgkmcnt(" #n ")" ::: "memory")
; template <class Epi, class Sched, bool ALIGN_EPI = false, bool SP2 = false>
; __device__ __forceinline__ void gemm_phase(PG8_LAS unsigned char* lds, const Gemm g, const Sched& S, const Epi& E) {
;     ...
;             const bool last = (t == nt - 2);
;             const char* a1 = cA + (size_t)(t + 1) * kstep;
;             const char* a2 = last ? nA : cA + (size_t)(t + 2) * kstep; const char* b2 = last ? nB : cB + (size_t)(t + 2) * kstep;
;             const char* a3 = a2 + kstep; const char* b3 = b2 + kstep;
;             if (last && has_next) S.a_ready(nxt);
;             if constexpr (SP2) {
;             PG8_LDB(B0, 0, 0); PG8_LDB(B1, 0, 1); PG8_SCHED; PG8_LDA(At, 0, 0); PG8_STAGE(PG8_SA(1, 1), a1 + hstep, voffA);
;             PG8_WAIT_V(8); PG8_WAIT_L(0); PG8_BAR; PG8_MMA(0, 0, At, B0); PG8_MMA(0, 1, At, B1); PG8_BAR; PG8_SCHED;
;             PG8_LDA(At, 0, 1); PG8_STAGE(PG8_SB(0, 0), b2, voffB); PG8_STAGE(PG8_SB(0, 1), b2 + hstep, voffB); PG8_STAGE(PG8_SA(0, 0), a2, voffA);
;             PG8_WAIT_V(8); PG8_WAIT_L(0); PG8_BAR; PG8_MMA(1, 0, At, B0); PG8_MMA(1, 1, At, B1); PG8_BAR; PG8_SCHED;
.LBB0_244:
	ds_read_b128 v[128:131], v169
	ds_read_b128 v[156:159], v169 offset:1024
	ds_read_b128 v[160:163], v169 offset:2048
	ds_read_b128 v[164:167], v169 offset:3072
	ds_read_b128 v[176:179], v170
	ds_read_b128 v[180:183], v170 offset:1024
	ds_read_b128 v[188:191], v170 offset:2048
	ds_read_b128 v[192:195], v170 offset:3072
	s_add_u32 s0, s4, 0xfff80080
	s_addc_u32 s1, s5, -1
	s_cmp_eq_u32 vcc_hi, 28
	s_cselect_b32 s9, s41, s1
	s_cselect_b32 s8, s51, s0
	s_cselect_b32 s7, s43, vcc_lo
	s_cselect_b32 s6, s56, s57
	s_add_i32 m0, s49, 0xc000
	ds_read_b128 v[196:199], v171
	ds_read_b128 v[200:203], v171 offset:1024
	ds_read_b128 v[204:207], v171 offset:2048
	ds_read_b128 v[208:211], v171 offset:3072
	ds_read_b128 v[212:215], v171 offset:4096
	ds_read_b128 v[216:219], v171 offset:5120
	ds_read_b128 v[220:223], v171 offset:6144
	global_load_lds_dwordx4 v144, s[4:5]
	s_add_i32 m0, s49, 0xe000
	ds_read_b128 v[224:227], v171 offset:7168
	global_load_lds_dwordx4 v146, s[4:5]
	s_waitcnt vmcnt(8)
	s_waitcnt lgkmcnt(0)
	s_barrier
	s_setprio 1
	s_waitcnt lgkmcnt(0)
	v_mfma_f32_16x16x32_bf16 v[124:127], v[128:131], v[196:199], v[124:127]
	v_mfma_f32_16x16x32_bf16 v[120:123], v[160:163], v[196:199], v[120:123]
	v_mfma_f32_16x16x32_bf16 v[108:111], v[128:131], v[204:207], v[108:111]
	v_mfma_f32_16x16x32_bf16 v[104:107], v[160:163], v[204:207], v[104:107]
	v_mfma_f32_16x16x32_bf16 v[92:95], v[128:131], v[212:215], v[92:95]
	v_mfma_f32_16x16x32_bf16 v[88:91], v[160:163], v[212:215], v[88:91]
	v_mfma_f32_16x16x32_bf16 v[76:79], v[128:131], v[220:223], v[76:79]
	v_mfma_f32_16x16x32_bf16 v[72:75], v[160:163], v[220:223], v[72:75]
	v_mfma_f32_16x16x32_bf16 v[124:127], v[156:159], v[200:203], v[124:127]
	v_mfma_f32_16x16x32_bf16 v[120:123], v[164:167], v[200:203], v[120:123]
	v_mfma_f32_16x16x32_bf16 v[108:111], v[156:159], v[208:211], v[108:111]
	v_mfma_f32_16x16x32_bf16 v[104:107], v[164:167], v[208:211], v[104:107]
	v_mfma_f32_16x16x32_bf16 v[92:95], v[156:159], v[216:219], v[92:95]
	v_mfma_f32_16x16x32_bf16 v[88:91], v[164:167], v[216:219], v[88:91]
	v_mfma_f32_16x16x32_bf16 v[76:79], v[156:159], v[224:227], v[76:79]
	v_mfma_f32_16x16x32_bf16 v[72:75], v[164:167], v[224:227], v[72:75]
	v_mfma_f32_16x16x32_bf16 v[116:119], v[176:179], v[196:199], v[116:119]
	v_mfma_f32_16x16x32_bf16 v[112:115], v[188:191], v[196:199], v[112:115]
	v_mfma_f32_16x16x32_bf16 v[100:103], v[176:179], v[204:207], v[100:103]
	v_mfma_f32_16x16x32_bf16 v[96:99], v[188:191], v[204:207], v[96:99]
	v_mfma_f32_16x16x32_bf16 v[84:87], v[176:179], v[212:215], v[84:87]
	v_mfma_f32_16x16x32_bf16 v[80:83], v[188:191], v[212:215], v[80:83]
	v_mfma_f32_16x16x32_bf16 v[68:71], v[176:179], v[220:223], v[68:71]
	v_mfma_f32_16x16x32_bf16 v[64:67], v[188:191], v[220:223], v[64:67]
	v_mfma_f32_16x16x32_bf16 v[116:119], v[180:183], v[200:203], v[116:119]
	v_mfma_f32_16x16x32_bf16 v[112:115], v[192:195], v[200:203], v[112:115]
	v_mfma_f32_16x16x32_bf16 v[100:103], v[180:183], v[208:211], v[100:103]
	v_mfma_f32_16x16x32_bf16 v[96:99], v[192:195], v[208:211], v[96:99]
	v_mfma_f32_16x16x32_bf16 v[84:87], v[180:183], v[216:219], v[84:87]
	v_mfma_f32_16x16x32_bf16 v[80:83], v[192:195], v[216:219], v[80:83]
	v_mfma_f32_16x16x32_bf16 v[68:71], v[180:183], v[224:227], v[68:71]
	v_mfma_f32_16x16x32_bf16 v[64:67], v[192:195], v[224:227], v[64:67]
	s_setprio 0
	s_barrier
	s_add_u32 s98, s6, s26
	s_addc_u32 s99, s7, s27
	s_add_u32 s100, s8, s26
	s_addc_u32 s101, s9, s27
	s_add_i32 s0, s70, s58
	s_mov_b32 m0, s0
	ds_read_b128 v[196:199], v171 offset:16384
	ds_read_b128 v[200:203], v171 offset:17408
	ds_read_b128 v[204:207], v171 offset:18432
	ds_read_b128 v[208:211], v171 offset:19456
	global_load_lds_dwordx4 v136, s[6:7]
	s_add_i32 m0, s0, 0x2000
	s_add_u32 s0, s6, 0x80000
	s_addc_u32 s1, s7, 0
	s_add_i32 s83, s72, s58
	global_load_lds_dwordx4 v140, s[6:7]
	s_mov_b32 m0, s83
	ds_read_b128 v[224:227], v171 offset:23552
	global_load_lds_dwordx4 v136, s[0:1]
	s_add_i32 m0, s83, 0x2000
	ds_read_b128 v[220:223], v171 offset:22528
	global_load_lds_dwordx4 v140, s[0:1]
	s_mov_b32 m0, s49
	ds_read_b128 v[216:219], v171 offset:21504
	global_load_lds_dwordx4 v134, s[8:9]
	s_mov_b32 m0, s59
	ds_read_b128 v[212:215], v171 offset:20480
	global_load_lds_dwordx4 v138, s[8:9]
	s_waitcnt vmcnt(8)
	s_waitcnt lgkmcnt(0)
	s_barrier
	s_setprio 1
	s_waitcnt lgkmcnt(0)
	v_mfma_f32_16x16x32_bf16 v[60:63], v[128:131], v[196:199], v[60:63]
	v_mfma_f32_16x16x32_bf16 v[56:59], v[160:163], v[196:199], v[56:59]
	v_mfma_f32_16x16x32_bf16 v[44:47], v[128:131], v[204:207], v[44:47]
	v_mfma_f32_16x16x32_bf16 v[40:43], v[160:163], v[204:207], v[40:43]
	v_mfma_f32_16x16x32_bf16 v[28:31], v[128:131], v[212:215], v[28:31]
	v_mfma_f32_16x16x32_bf16 v[24:27], v[160:163], v[212:215], v[24:27]
	v_mfma_f32_16x16x32_bf16 v[12:15], v[128:131], v[220:223], v[12:15]
	v_mfma_f32_16x16x32_bf16 v[8:11], v[160:163], v[220:223], v[8:11]
	v_mfma_f32_16x16x32_bf16 v[60:63], v[156:159], v[200:203], v[60:63]
	v_mfma_f32_16x16x32_bf16 v[56:59], v[164:167], v[200:203], v[56:59]
	v_mfma_f32_16x16x32_bf16 v[44:47], v[156:159], v[208:211], v[44:47]
	v_mfma_f32_16x16x32_bf16 v[40:43], v[164:167], v[208:211], v[40:43]
	v_mfma_f32_16x16x32_bf16 v[28:31], v[156:159], v[216:219], v[28:31]
	v_mfma_f32_16x16x32_bf16 v[24:27], v[164:167], v[216:219], v[24:27]
	v_mfma_f32_16x16x32_bf16 v[12:15], v[156:159], v[224:227], v[12:15]
	v_mfma_f32_16x16x32_bf16 v[8:11], v[164:167], v[224:227], v[8:11]
	v_mfma_f32_16x16x32_bf16 v[52:55], v[176:179], v[196:199], v[52:55]
	v_mfma_f32_16x16x32_bf16 v[48:51], v[188:191], v[196:199], v[48:51]
	v_mfma_f32_16x16x32_bf16 v[36:39], v[176:179], v[204:207], v[36:39]
	v_mfma_f32_16x16x32_bf16 v[32:35], v[188:191], v[204:207], v[32:35]
	v_mfma_f32_16x16x32_bf16 v[20:23], v[176:179], v[212:215], v[20:23]
	v_mfma_f32_16x16x32_bf16 v[16:19], v[188:191], v[212:215], v[16:19]
	v_mfma_f32_16x16x32_bf16 v[4:7], v[176:179], v[220:223], v[4:7]
	v_mfma_f32_16x16x32_bf16 v[0:3], v[188:191], v[220:223], v[0:3]
	v_mfma_f32_16x16x32_bf16 v[52:55], v[180:183], v[200:203], v[52:55]
	v_mfma_f32_16x16x32_bf16 v[48:51], v[192:195], v[200:203], v[48:51]
	v_mfma_f32_16x16x32_bf16 v[36:39], v[180:183], v[208:211], v[36:39]
	v_mfma_f32_16x16x32_bf16 v[32:35], v[192:195], v[208:211], v[32:35]
	v_mfma_f32_16x16x32_bf16 v[20:23], v[180:183], v[216:219], v[20:23]
	v_mfma_f32_16x16x32_bf16 v[16:19], v[192:195], v[216:219], v[16:19]
	v_mfma_f32_16x16x32_bf16 v[4:7], v[180:183], v[224:227], v[4:7]
	v_mfma_f32_16x16x32_bf16 v[0:3], v[192:195], v[224:227], v[0:3]
	s_setprio 0
	s_barrier
; #define PG8_STAGE(bufoff, gbase, voff) do { _Pragma("unroll") for (int _i = 0; _i < 2; ++_i) \
;         __builtin_amdgcn_global_load_lds((const unsigned*)((const char*)(gbase) + (voff)[_i]), (PG8_LAS unsigned*)(lds + (bufoff) + ldsw + _i * 8192), 16, 0, 0); } while (0)
; #define PG8_LDA(dst, b, h) do { _Pragma("unroll") for (int m = 0; m < 4; ++m) _Pragma("unroll") for (int k = 0; k < 2; ++k) dst[m][k] = *(const PG8_LAS bf16x8*)(lds + PG8_SA(b, h) + aoff + m * 2048 + k * 1024); } while (0)
; #define PG8_LDB(dst, b, h) do { _Pragma("unroll") for (int n = 0; n < 2; ++n) _Pragma("unroll") for (int k = 0; k < 2; ++k) dst[n][k] = *(const PG8_LAS bf16x8*)(lds + PG8_SB(b, h) + boff + n * 2048 + k * 1024); } while (0)
; #define PG8_MMA(ai, bj, At, Bt) do { __builtin_amdgcn_s_setprio(1); _Pragma("unroll") for (int m = 0; m < 4; ++m) _Pragma("unroll") for (int n = 0; n < 2; ++n) _Pragma("unroll") for (int k = 0; k < 2; ++k) \
;         acc[ai][bj][m][n] = __builtin_amdgcn_mfma_f32_16x16x32_bf16(Bt[n][k], At[m][k], acc[ai][bj][m][n], 0, 0, 0); __builtin_amdgcn_s_setprio(0); } while (0)
; #define PG8_WAIT_V(n) asm volatile("s_waitcnt vmcnt(" #n ")" ::: "memory")
; #define PG8_WAIT_L(n) asm volatile("s_waitcnt lgkmcnt(" #n ")" ::: "memory")
; #define PG8_BAR __builtin_amdgcn_s_barrier()
; #define PG8_SCHED __builtin_amdgcn_sched_barrier(0)
; template <class Epi, class Sched, bool ALIGN_EPI = false, bool SP2 = false>
; __device__ __forceinline__ void gemm_phase(PG8_LAS unsigned char* lds, const Gemm g, const Sched& S, const Epi& E) {
;     ...
;             PG8_LDB(B0, 1, 0); PG8_LDB(B1, 1, 1); PG8_SCHED; PG8_LDA(At, 1, 0); PG8_STAGE(PG8_SA(0, 1), a2 + hstep, voffA);
;             PG8_WAIT_V(8); PG8_WAIT_L(0); PG8_BAR; PG8_MMA(0, 0, At, B0); PG8_MMA(0, 1, At, B1); PG8_BAR; PG8_SCHED;
;             PG8_LDA(At, 1, 1); PG8_STAGE(PG8_SB(1, 0), b3, voffB); PG8_STAGE(PG8_SB(1, 1), b3 + hstep, voffB); PG8_STAGE(PG8_SA(1, 0), a3, voffA);
;             PG8_WAIT_V(8); PG8_WAIT_L(0); PG8_BAR; PG8_MMA(1, 0, At, B0); PG8_MMA(1, 1, At, B1); PG8_BAR; PG8_SCHED;
	s_add_i32 s83, 0, 0x18000
	v_add_u32_e32 v142, s83, v168
	s_add_i32 s88, 0, 0x1c000
	ds_read_b128 v[128:131], v142
	ds_read_b128 v[156:159], v142 offset:1024
	ds_read_b128 v[160:163], v142 offset:2048
	ds_read_b128 v[164:167], v142 offset:3072
	v_add_u32_e32 v142, s88, v168
	ds_read_b128 v[176:179], v142
	ds_read_b128 v[180:183], v142 offset:1024
	ds_read_b128 v[188:191], v142 offset:2048
	ds_read_b128 v[192:195], v142 offset:3072
	s_add_u32 s0, s8, 0x80000
	s_addc_u32 s1, s9, 0
	s_mov_b32 m0, s73
	ds_read_b128 v[196:199], v171 offset:32768
	ds_read_b128 v[200:203], v171 offset:33792
	ds_read_b128 v[204:207], v171 offset:34816
	ds_read_b128 v[208:211], v171 offset:35840
	ds_read_b128 v[212:215], v171 offset:36864
	ds_read_b128 v[216:219], v171 offset:37888
	ds_read_b128 v[220:223], v171 offset:38912
	global_load_lds_dwordx4 v134, s[0:1]
	s_mov_b32 m0, s74
	ds_read_b128 v[224:227], v171 offset:39936
	global_load_lds_dwordx4 v138, s[0:1]
	s_waitcnt vmcnt(8)
	s_waitcnt lgkmcnt(0)
	s_barrier
	s_setprio 1
	s_waitcnt lgkmcnt(0)
	v_mfma_f32_16x16x32_bf16 v[124:127], v[128:131], v[196:199], v[124:127]
	v_mfma_f32_16x16x32_bf16 v[120:123], v[160:163], v[196:199], v[120:123]
	v_mfma_f32_16x16x32_bf16 v[108:111], v[128:131], v[204:207], v[108:111]
	v_mfma_f32_16x16x32_bf16 v[104:107], v[160:163], v[204:207], v[104:107]
	v_mfma_f32_16x16x32_bf16 v[92:95], v[128:131], v[212:215], v[92:95]
	v_mfma_f32_16x16x32_bf16 v[88:91], v[160:163], v[212:215], v[88:91]
	v_mfma_f32_16x16x32_bf16 v[76:79], v[128:131], v[220:223], v[76:79]
	v_mfma_f32_16x16x32_bf16 v[72:75], v[160:163], v[220:223], v[72:75]
	v_mfma_f32_16x16x32_bf16 v[124:127], v[156:159], v[200:203], v[124:127]
	v_mfma_f32_16x16x32_bf16 v[120:123], v[164:167], v[200:203], v[120:123]
	v_mfma_f32_16x16x32_bf16 v[108:111], v[156:159], v[208:211], v[108:111]
	v_mfma_f32_16x16x32_bf16 v[104:107], v[164:167], v[208:211], v[104:107]
	v_mfma_f32_16x16x32_bf16 v[92:95], v[156:159], v[216:219], v[92:95]
	v_mfma_f32_16x16x32_bf16 v[88:91], v[164:167], v[216:219], v[88:91]
	v_mfma_f32_16x16x32_bf16 v[76:79], v[156:159], v[224:227], v[76:79]
	v_mfma_f32_16x16x32_bf16 v[72:75], v[164:167], v[224:227], v[72:75]
	v_mfma_f32_16x16x32_bf16 v[116:119], v[176:179], v[196:199], v[116:119]
	v_mfma_f32_16x16x32_bf16 v[112:115], v[188:191], v[196:199], v[112:115]
	v_mfma_f32_16x16x32_bf16 v[100:103], v[176:179], v[204:207], v[100:103]
	v_mfma_f32_16x16x32_bf16 v[96:99], v[188:191], v[204:207], v[96:99]
	v_mfma_f32_16x16x32_bf16 v[84:87], v[176:179], v[212:215], v[84:87]
	v_mfma_f32_16x16x32_bf16 v[80:83], v[188:191], v[212:215], v[80:83]
	v_mfma_f32_16x16x32_bf16 v[68:71], v[176:179], v[220:223], v[68:71]
	v_mfma_f32_16x16x32_bf16 v[64:67], v[188:191], v[220:223], v[64:67]
	v_mfma_f32_16x16x32_bf16 v[116:119], v[180:183], v[200:203], v[116:119]
	v_mfma_f32_16x16x32_bf16 v[112:115], v[192:195], v[200:203], v[112:115]
	v_mfma_f32_16x16x32_bf16 v[100:103], v[180:183], v[208:211], v[100:103]
	v_mfma_f32_16x16x32_bf16 v[96:99], v[192:195], v[208:211], v[96:99]
	v_mfma_f32_16x16x32_bf16 v[84:87], v[180:183], v[216:219], v[84:87]
	v_mfma_f32_16x16x32_bf16 v[80:83], v[192:195], v[216:219], v[80:83]
	v_mfma_f32_16x16x32_bf16 v[68:71], v[180:183], v[224:227], v[68:71]
	v_mfma_f32_16x16x32_bf16 v[64:67], v[192:195], v[224:227], v[64:67]
	s_setprio 0
	s_barrier
	s_add_i32 s0, s83, s58
	s_mov_b32 m0, s0
	ds_read_b128 v[196:199], v171 offset:49152
	ds_read_b128 v[200:203], v171 offset:50176
	ds_read_b128 v[204:207], v171 offset:51200
	ds_read_b128 v[208:211], v171 offset:52224
	global_load_lds_dwordx4 v136, s[98:99]
	s_add_i32 m0, s0, 0x2000
	s_add_u32 s0, s6, 0x80080
	s_addc_u32 s1, s7, 0
	s_add_i32 s6, s88, s58
	global_load_lds_dwordx4 v140, s[98:99]
	s_mov_b32 m0, s6
	ds_read_b128 v[224:227], v171 offset:56320
	global_load_lds_dwordx4 v136, s[0:1]
	s_add_i32 m0, s6, 0x2000
	ds_read_b128 v[220:223], v171 offset:55296
	global_load_lds_dwordx4 v140, s[0:1]
	s_mov_b32 m0, s78
	ds_read_b128 v[216:219], v171 offset:54272
	global_load_lds_dwordx4 v134, s[100:101]
	s_mov_b32 m0, s79
	ds_read_b128 v[212:215], v171 offset:53248
	global_load_lds_dwordx4 v138, s[100:101]
	s_waitcnt vmcnt(8)
	s_waitcnt lgkmcnt(0)
	s_barrier
	s_setprio 1
	s_waitcnt lgkmcnt(0)
	v_mfma_f32_16x16x32_bf16 v[60:63], v[128:131], v[196:199], v[60:63]
	v_mfma_f32_16x16x32_bf16 v[56:59], v[160:163], v[196:199], v[56:59]
	v_mfma_f32_16x16x32_bf16 v[44:47], v[128:131], v[204:207], v[44:47]
	v_mfma_f32_16x16x32_bf16 v[40:43], v[160:163], v[204:207], v[40:43]
	v_mfma_f32_16x16x32_bf16 v[28:31], v[128:131], v[212:215], v[28:31]
	v_mfma_f32_16x16x32_bf16 v[24:27], v[160:163], v[212:215], v[24:27]
	v_mfma_f32_16x16x32_bf16 v[12:15], v[128:131], v[220:223], v[12:15]
	v_mfma_f32_16x16x32_bf16 v[8:11], v[160:163], v[220:223], v[8:11]
	v_mfma_f32_16x16x32_bf16 v[60:63], v[156:159], v[200:203], v[60:63]
	v_mfma_f32_16x16x32_bf16 v[56:59], v[164:167], v[200:203], v[56:59]
	v_mfma_f32_16x16x32_bf16 v[44:47], v[156:159], v[208:211], v[44:47]
	v_mfma_f32_16x16x32_bf16 v[40:43], v[164:167], v[208:211], v[40:43]
	v_mfma_f32_16x16x32_bf16 v[28:31], v[156:159], v[216:219], v[28:31]
	v_mfma_f32_16x16x32_bf16 v[24:27], v[164:167], v[216:219], v[24:27]
	v_mfma_f32_16x16x32_bf16 v[12:15], v[156:159], v[224:227], v[12:15]
	v_mfma_f32_16x16x32_bf16 v[8:11], v[164:167], v[224:227], v[8:11]
	v_mfma_f32_16x16x32_bf16 v[52:55], v[176:179], v[196:199], v[52:55]
	v_mfma_f32_16x16x32_bf16 v[48:51], v[188:191], v[196:199], v[48:51]
	v_mfma_f32_16x16x32_bf16 v[36:39], v[176:179], v[204:207], v[36:39]
	v_mfma_f32_16x16x32_bf16 v[32:35], v[188:191], v[204:207], v[32:35]
	v_mfma_f32_16x16x32_bf16 v[20:23], v[176:179], v[212:215], v[20:23]
	v_mfma_f32_16x16x32_bf16 v[16:19], v[188:191], v[212:215], v[16:19]
	v_mfma_f32_16x16x32_bf16 v[4:7], v[176:179], v[220:223], v[4:7]
	v_mfma_f32_16x16x32_bf16 v[0:3], v[188:191], v[220:223], v[0:3]
	v_mfma_f32_16x16x32_bf16 v[52:55], v[180:183], v[200:203], v[52:55]
	v_mfma_f32_16x16x32_bf16 v[48:51], v[192:195], v[200:203], v[48:51]
	v_mfma_f32_16x16x32_bf16 v[36:39], v[180:183], v[208:211], v[36:39]
	v_mfma_f32_16x16x32_bf16 v[32:35], v[192:195], v[208:211], v[32:35]
	v_mfma_f32_16x16x32_bf16 v[20:23], v[180:183], v[216:219], v[20:23]
	v_mfma_f32_16x16x32_bf16 v[16:19], v[192:195], v[216:219], v[16:19]
	v_mfma_f32_16x16x32_bf16 v[4:7], v[180:183], v[224:227], v[4:7]
	v_mfma_f32_16x16x32_bf16 v[0:3], v[192:195], v[224:227], v[0:3]
	s_setprio 0
	s_barrier
	s_add_i32 vcc_hi, vcc_hi, 2
	s_add_u32 s4, s4, 0x100
	s_addc_u32 s5, s5, 0
	s_add_u32 s57, s57, 0x100
	s_addc_u32 vcc_lo, vcc_lo, 0
	s_cmp_gt_u32 vcc_hi, 29
	s_cbranch_scc0 .LBB0_244
	s_and_b64 vcc, exec, s[28:29]
	s_cbranch_vccz .LBB0_247
	s_barrier

; #define PG8_STAGE(bufoff, gbase, voff) do { _Pragma("unroll") for (int _i = 0; _i < 2; ++_i) \
;         __builtin_amdgcn_global_load_lds((const unsigned*)((const char*)(gbase) + (voff)[_i]), (PG8_LAS unsigned*)(lds + (bufoff) + ldsw + _i * 8192), 16, 0, 0); } while (0)
; #define PG8_LDA(dst, b, h) do { _Pragma("unroll") for (int m = 0; m < 4; ++m) _Pragma("unroll") for (int k = 0; k < 2; ++k) dst[m][k] = *(const PG8_LAS bf16x8*)(lds + PG8_SA(b, h) + aoff + m * 2048 + k * 1024); } while (0)
; #define PG8_LDB(dst, b, h) do { _Pragma("unroll") for (int n = 0; n < 2; ++n) _Pragma("unroll") for (int k = 0; k < 2; ++k) dst[n][k] = *(const PG8_LAS bf16x8*)(lds + PG8_SB(b, h) + boff + n * 2048 + k * 1024); } while (0)
; #define PG8_MMA(ai, bj, At, Bt) do { __builtin_amdgcn_s_setprio(1); _Pragma("unroll") for (int m = 0; m < 4; ++m) _Pragma("unroll") for (int n = 0; n < 2; ++n) _Pragma("unroll") for (int k = 0; k < 2; ++k) \
;         acc[ai][bj][m][n] = __builtin_amdgcn_mfma_f32_16x16x32_bf16(Bt[n][k], At[m][k], acc[ai][bj][m][n], 0, 0, 0); __builtin_amdgcn_s_setprio(0); } while (0)
; #define PG8_WAIT_V(n) asm volatile("s_waitcnt vmcnt(" #n ")" ::: "memory")
; #define PG8_WAIT_L(n) asm volatile("s_waitcnt lgkmcnt(" #n ")" ::: "memory")
; template <class Epi, class Sched, bool ALIGN_EPI = false, bool SP2 = false>
; __device__ __forceinline__ void gemm_phase(PG8_LAS unsigned char* lds, const Gemm g, const Sched& S, const Epi& E) {
;     ...
;             const bool last = (t == nt - 2);
;             const char* a1 = cA + (size_t)(t + 1) * kstep;
;             const char* a2 = last ? nA : cA + (size_t)(t + 2) * kstep; const char* b2 = last ? nB : cB + (size_t)(t + 2) * kstep;
;             const char* a3 = a2 + kstep; const char* b3 = b2 + kstep;
;             if (last && has_next) S.a_ready(nxt);
;             if constexpr (SP2) {
;             PG8_LDB(B0, 0, 0); PG8_LDB(B1, 0, 1); PG8_SCHED; PG8_LDA(At, 0, 0); PG8_STAGE(PG8_SA(1, 1), a1 + hstep, voffA);
;             PG8_WAIT_V(8); PG8_WAIT_L(0); PG8_BAR; PG8_MMA(0, 0, At, B0); PG8_MMA(0, 1, At, B1); PG8_BAR; PG8_SCHED;
;             PG8_LDA(At, 0, 1); PG8_STAGE(PG8_SB(0, 0), b2, voffB); PG8_STAGE(PG8_SB(0, 1), b2 + hstep, voffB); PG8_STAGE(PG8_SA(0, 0), a2, voffA);
;             PG8_WAIT_V(8); PG8_WAIT_L(0); PG8_BAR; PG8_MMA(1, 0, At, B0); PG8_MMA(1, 1, At, B1); PG8_BAR; PG8_SCHED;
.LBB0_637:
	ds_read_b128 v[144:147], v153
	ds_read_b128 v[158:161], v153 offset:1024
	ds_read_b128 v[162:165], v153 offset:2048
	ds_read_b128 v[166:169], v153 offset:3072
	ds_read_b128 v[170:173], v154
	ds_read_b128 v[174:177], v154 offset:1024
	ds_read_b128 v[178:181], v154 offset:2048
	ds_read_b128 v[182:185], v154 offset:3072
	s_add_u32 s30, s28, 0xfff80080
	s_addc_u32 s31, s29, -1
	s_cmp_eq_u32 s50, 28
	s_cselect_b32 s35, s7, s31
	s_cselect_b32 s34, s21, s30
	s_cselect_b32 s31, s19, s49
	s_cselect_b32 s30, s47, s48
	s_add_i32 m0, s1, 0xc000
	ds_read_b128 v[188:191], v155
	ds_read_b128 v[192:195], v155 offset:1024
	ds_read_b128 v[196:199], v155 offset:2048
	ds_read_b128 v[200:203], v155 offset:3072
	ds_read_b128 v[204:207], v155 offset:4096
	ds_read_b128 v[208:211], v155 offset:5120
	ds_read_b128 v[212:215], v155 offset:6144
	global_load_lds_dwordx4 v136, s[28:29]
	s_add_i32 m0, s1, 0xe000
	ds_read_b128 v[216:219], v155 offset:7168
	global_load_lds_dwordx4 v138, s[28:29]
	s_waitcnt vmcnt(8)
	s_waitcnt lgkmcnt(0)
	s_barrier
	s_setprio 1
	s_waitcnt lgkmcnt(0)
	v_mfma_f32_16x16x32_bf16 v[124:127], v[144:147], v[188:191], v[124:127]
	v_mfma_f32_16x16x32_bf16 v[120:123], v[162:165], v[188:191], v[120:123]
	v_mfma_f32_16x16x32_bf16 v[108:111], v[144:147], v[196:199], v[108:111]
	v_mfma_f32_16x16x32_bf16 v[104:107], v[162:165], v[196:199], v[104:107]
	v_mfma_f32_16x16x32_bf16 v[92:95], v[144:147], v[204:207], v[92:95]
	v_mfma_f32_16x16x32_bf16 v[88:91], v[162:165], v[204:207], v[88:91]
	v_mfma_f32_16x16x32_bf16 v[76:79], v[144:147], v[212:215], v[76:79]
	v_mfma_f32_16x16x32_bf16 v[72:75], v[162:165], v[212:215], v[72:75]
	v_mfma_f32_16x16x32_bf16 v[124:127], v[158:161], v[192:195], v[124:127]
	v_mfma_f32_16x16x32_bf16 v[120:123], v[166:169], v[192:195], v[120:123]
	v_mfma_f32_16x16x32_bf16 v[108:111], v[158:161], v[200:203], v[108:111]
	v_mfma_f32_16x16x32_bf16 v[104:107], v[166:169], v[200:203], v[104:107]
	v_mfma_f32_16x16x32_bf16 v[92:95], v[158:161], v[208:211], v[92:95]
	v_mfma_f32_16x16x32_bf16 v[88:91], v[166:169], v[208:211], v[88:91]
	v_mfma_f32_16x16x32_bf16 v[76:79], v[158:161], v[216:219], v[76:79]
	v_mfma_f32_16x16x32_bf16 v[72:75], v[166:169], v[216:219], v[72:75]
	v_mfma_f32_16x16x32_bf16 v[116:119], v[170:173], v[188:191], v[116:119]
	v_mfma_f32_16x16x32_bf16 v[112:115], v[178:181], v[188:191], v[112:115]
	v_mfma_f32_16x16x32_bf16 v[100:103], v[170:173], v[196:199], v[100:103]
	v_mfma_f32_16x16x32_bf16 v[96:99], v[178:181], v[196:199], v[96:99]
	v_mfma_f32_16x16x32_bf16 v[84:87], v[170:173], v[204:207], v[84:87]
	v_mfma_f32_16x16x32_bf16 v[80:83], v[178:181], v[204:207], v[80:83]
	v_mfma_f32_16x16x32_bf16 v[68:71], v[170:173], v[212:215], v[68:71]
	v_mfma_f32_16x16x32_bf16 v[64:67], v[178:181], v[212:215], v[64:67]
	v_mfma_f32_16x16x32_bf16 v[116:119], v[174:177], v[192:195], v[116:119]
	v_mfma_f32_16x16x32_bf16 v[112:115], v[182:185], v[192:195], v[112:115]
	v_mfma_f32_16x16x32_bf16 v[100:103], v[174:177], v[200:203], v[100:103]
	v_mfma_f32_16x16x32_bf16 v[96:99], v[182:185], v[200:203], v[96:99]
	v_mfma_f32_16x16x32_bf16 v[84:87], v[174:177], v[208:211], v[84:87]
	v_mfma_f32_16x16x32_bf16 v[80:83], v[182:185], v[208:211], v[80:83]
	v_mfma_f32_16x16x32_bf16 v[68:71], v[174:177], v[216:219], v[68:71]
	v_mfma_f32_16x16x32_bf16 v[64:67], v[182:185], v[216:219], v[64:67]
	s_setprio 0
	s_barrier
	s_add_u32 s98, s30, s14
	s_addc_u32 s99, s31, s15
	s_add_u32 s100, s34, s14
	s_addc_u32 s101, s35, s15
	s_add_i32 s51, s45, s0
	s_mov_b32 m0, s51
	ds_read_b128 v[188:191], v155 offset:16384
	ds_read_b128 v[192:195], v155 offset:17408
	ds_read_b128 v[196:199], v155 offset:18432
	ds_read_b128 v[200:203], v155 offset:19456
	ds_read_b128 v[204:207], v155 offset:20480
	ds_read_b128 v[208:211], v155 offset:21504
	ds_read_b128 v[212:215], v155 offset:22528
	ds_read_b128 v[216:219], v155 offset:23552
	global_load_lds_dwordx4 v130, s[30:31]
	s_add_i32 m0, s51, 0x2000
	s_add_u32 s54, s30, 0x80000
	s_addc_u32 s55, s31, 0
	s_add_i32 s51, s46, s0
	global_load_lds_dwordx4 v134, s[30:31]
	s_mov_b32 m0, s51
	v_lshl_add_u64 v[224:225], s[34:35], 0, v[132:133]
	global_load_lds_dwordx4 v130, s[54:55]
	s_add_i32 m0, s51, 0x2000
	s_nop 0
	global_load_lds_dwordx4 v134, s[54:55]
	s_mov_b32 m0, s1
	s_nop 0
	global_load_lds_dwordx4 v128, s[34:35]
	s_mov_b32 m0, s27
	s_nop 0
	global_load_lds_dwordx4 v132, s[34:35]
	s_waitcnt vmcnt(8)
	s_waitcnt lgkmcnt(0)
	s_barrier
	s_setprio 1
	s_waitcnt lgkmcnt(0)
	v_mfma_f32_16x16x32_bf16 v[60:63], v[144:147], v[188:191], v[60:63]
	v_mfma_f32_16x16x32_bf16 v[56:59], v[162:165], v[188:191], v[56:59]
	v_mfma_f32_16x16x32_bf16 v[44:47], v[144:147], v[196:199], v[44:47]
	v_mfma_f32_16x16x32_bf16 v[40:43], v[162:165], v[196:199], v[40:43]
	v_mfma_f32_16x16x32_bf16 v[28:31], v[144:147], v[204:207], v[28:31]
	v_mfma_f32_16x16x32_bf16 v[24:27], v[162:165], v[204:207], v[24:27]
	v_mfma_f32_16x16x32_bf16 v[12:15], v[144:147], v[212:215], v[12:15]
	v_mfma_f32_16x16x32_bf16 v[8:11], v[162:165], v[212:215], v[8:11]
	v_mfma_f32_16x16x32_bf16 v[60:63], v[158:161], v[192:195], v[60:63]
	v_mfma_f32_16x16x32_bf16 v[56:59], v[166:169], v[192:195], v[56:59]
	v_mfma_f32_16x16x32_bf16 v[44:47], v[158:161], v[200:203], v[44:47]
	v_mfma_f32_16x16x32_bf16 v[40:43], v[166:169], v[200:203], v[40:43]
	v_mfma_f32_16x16x32_bf16 v[28:31], v[158:161], v[208:211], v[28:31]
	v_mfma_f32_16x16x32_bf16 v[24:27], v[166:169], v[208:211], v[24:27]
	v_mfma_f32_16x16x32_bf16 v[12:15], v[158:161], v[216:219], v[12:15]
	v_mfma_f32_16x16x32_bf16 v[8:11], v[166:169], v[216:219], v[8:11]
	v_mfma_f32_16x16x32_bf16 v[52:55], v[170:173], v[188:191], v[52:55]
	v_mfma_f32_16x16x32_bf16 v[48:51], v[178:181], v[188:191], v[48:51]
	v_mfma_f32_16x16x32_bf16 v[36:39], v[170:173], v[196:199], v[36:39]
	v_mfma_f32_16x16x32_bf16 v[32:35], v[178:181], v[196:199], v[32:35]
	v_mfma_f32_16x16x32_bf16 v[20:23], v[170:173], v[204:207], v[20:23]
	v_mfma_f32_16x16x32_bf16 v[16:19], v[178:181], v[204:207], v[16:19]
	v_mfma_f32_16x16x32_bf16 v[4:7], v[170:173], v[212:215], v[4:7]
	v_mfma_f32_16x16x32_bf16 v[0:3], v[178:181], v[212:215], v[0:3]
	v_mfma_f32_16x16x32_bf16 v[52:55], v[174:177], v[192:195], v[52:55]
	v_mfma_f32_16x16x32_bf16 v[48:51], v[182:185], v[192:195], v[48:51]
	v_mfma_f32_16x16x32_bf16 v[36:39], v[174:177], v[200:203], v[36:39]
	v_mfma_f32_16x16x32_bf16 v[32:35], v[182:185], v[200:203], v[32:35]
	v_mfma_f32_16x16x32_bf16 v[20:23], v[174:177], v[208:211], v[20:23]
	v_mfma_f32_16x16x32_bf16 v[16:19], v[182:185], v[208:211], v[16:19]
	v_mfma_f32_16x16x32_bf16 v[4:7], v[174:177], v[216:219], v[4:7]
	v_mfma_f32_16x16x32_bf16 v[0:3], v[182:185], v[216:219], v[0:3]
	s_setprio 0
	s_barrier
; #define PG8_STAGE(bufoff, gbase, voff) do { _Pragma("unroll") for (int _i = 0; _i < 2; ++_i) \
;         __builtin_amdgcn_global_load_lds((const unsigned*)((const char*)(gbase) + (voff)[_i]), (PG8_LAS unsigned*)(lds + (bufoff) + ldsw + _i * 8192), 16, 0, 0); } while (0)
; #define PG8_LDA(dst, b, h) do { _Pragma("unroll") for (int m = 0; m < 4; ++m) _Pragma("unroll") for (int k = 0; k < 2; ++k) dst[m][k] = *(const PG8_LAS bf16x8*)(lds + PG8_SA(b, h) + aoff + m * 2048 + k * 1024); } while (0)
; #define PG8_LDB(dst, b, h) do { _Pragma("unroll") for (int n = 0; n < 2; ++n) _Pragma("unroll") for (int k = 0; k < 2; ++k) dst[n][k] = *(const PG8_LAS bf16x8*)(lds + PG8_SB(b, h) + boff + n * 2048 + k * 1024); } while (0)
; #define PG8_MMA(ai, bj, At, Bt) do { __builtin_amdgcn_s_setprio(1); _Pragma("unroll") for (int m = 0; m < 4; ++m) _Pragma("unroll") for (int n = 0; n < 2; ++n) _Pragma("unroll") for (int k = 0; k < 2; ++k) \
;         acc[ai][bj][m][n] = __builtin_amdgcn_mfma_f32_16x16x32_bf16(Bt[n][k], At[m][k], acc[ai][bj][m][n], 0, 0, 0); __builtin_amdgcn_s_setprio(0); } while (0)
; #define PG8_WAIT_V(n) asm volatile("s_waitcnt vmcnt(" #n ")" ::: "memory")
; #define PG8_WAIT_L(n) asm volatile("s_waitcnt lgkmcnt(" #n ")" ::: "memory")
; #define PG8_BAR __builtin_amdgcn_s_barrier()
; #define PG8_SCHED __builtin_amdgcn_sched_barrier(0)
; template <class Epi, class Sched, bool ALIGN_EPI = false, bool SP2 = false>
; __device__ __forceinline__ void gemm_phase(PG8_LAS unsigned char* lds, const Gemm g, const Sched& S, const Epi& E) {
;     ...
;             PG8_LDB(B0, 1, 0); PG8_LDB(B1, 1, 1); PG8_SCHED; PG8_LDA(At, 1, 0); PG8_STAGE(PG8_SA(0, 1), a2 + hstep, voffA);
;             PG8_WAIT_V(8); PG8_WAIT_L(0); PG8_BAR; PG8_MMA(0, 0, At, B0); PG8_MMA(0, 1, At, B1); PG8_BAR; PG8_SCHED;
;             PG8_LDA(At, 1, 1); PG8_STAGE(PG8_SB(1, 0), b3, voffB); PG8_STAGE(PG8_SB(1, 1), b3 + hstep, voffB); PG8_STAGE(PG8_SA(1, 0), a3, voffA);
;             PG8_WAIT_V(8); PG8_WAIT_L(0); PG8_BAR; PG8_MMA(1, 0, At, B0); PG8_MMA(1, 1, At, B1); PG8_BAR; PG8_SCHED;
	s_add_i32 s51, 0, 0x18000
	v_add_u32_e32 v157, s51, v152
	s_add_i32 s54, 0, 0x1c000
	ds_read_b128 v[144:147], v157
	ds_read_b128 v[158:161], v157 offset:1024
	ds_read_b128 v[162:165], v157 offset:2048
	ds_read_b128 v[166:169], v157 offset:3072
	v_add_u32_e32 v157, s54, v152
	ds_read_b128 v[170:173], v157
	ds_read_b128 v[174:177], v157 offset:1024
	ds_read_b128 v[178:181], v157 offset:2048
	ds_read_b128 v[182:185], v157 offset:3072
	s_add_u32 s34, s34, 0x80000
	s_addc_u32 s35, s35, 0
	s_mov_b32 m0, s36
	ds_read_b128 v[188:191], v155 offset:32768
	ds_read_b128 v[192:195], v155 offset:33792
	ds_read_b128 v[196:199], v155 offset:34816
	ds_read_b128 v[200:203], v155 offset:35840
	ds_read_b128 v[204:207], v155 offset:36864
	ds_read_b128 v[208:211], v155 offset:37888
	ds_read_b128 v[212:215], v155 offset:38912
	global_load_lds_dwordx4 v128, s[34:35]
	s_mov_b32 m0, s37
	ds_read_b128 v[216:219], v155 offset:39936
	global_load_lds_dwordx4 v132, s[34:35]
	s_waitcnt vmcnt(8)
	s_waitcnt lgkmcnt(0)
	s_barrier
	s_setprio 1
	s_waitcnt lgkmcnt(0)
	v_mfma_f32_16x16x32_bf16 v[124:127], v[144:147], v[188:191], v[124:127]
	v_mfma_f32_16x16x32_bf16 v[120:123], v[162:165], v[188:191], v[120:123]
	v_mfma_f32_16x16x32_bf16 v[108:111], v[144:147], v[196:199], v[108:111]
	v_mfma_f32_16x16x32_bf16 v[104:107], v[162:165], v[196:199], v[104:107]
	v_mfma_f32_16x16x32_bf16 v[92:95], v[144:147], v[204:207], v[92:95]
	v_mfma_f32_16x16x32_bf16 v[88:91], v[162:165], v[204:207], v[88:91]
	v_mfma_f32_16x16x32_bf16 v[76:79], v[144:147], v[212:215], v[76:79]
	v_mfma_f32_16x16x32_bf16 v[72:75], v[162:165], v[212:215], v[72:75]
	v_mfma_f32_16x16x32_bf16 v[124:127], v[158:161], v[192:195], v[124:127]
	v_mfma_f32_16x16x32_bf16 v[120:123], v[166:169], v[192:195], v[120:123]
	v_mfma_f32_16x16x32_bf16 v[108:111], v[158:161], v[200:203], v[108:111]
	v_mfma_f32_16x16x32_bf16 v[104:107], v[166:169], v[200:203], v[104:107]
	v_mfma_f32_16x16x32_bf16 v[92:95], v[158:161], v[208:211], v[92:95]
	v_mfma_f32_16x16x32_bf16 v[88:91], v[166:169], v[208:211], v[88:91]
	v_mfma_f32_16x16x32_bf16 v[76:79], v[158:161], v[216:219], v[76:79]
	v_mfma_f32_16x16x32_bf16 v[72:75], v[166:169], v[216:219], v[72:75]
	v_mfma_f32_16x16x32_bf16 v[116:119], v[170:173], v[188:191], v[116:119]
	v_mfma_f32_16x16x32_bf16 v[112:115], v[178:181], v[188:191], v[112:115]
	v_mfma_f32_16x16x32_bf16 v[100:103], v[170:173], v[196:199], v[100:103]
	v_mfma_f32_16x16x32_bf16 v[96:99], v[178:181], v[196:199], v[96:99]
	v_mfma_f32_16x16x32_bf16 v[84:87], v[170:173], v[204:207], v[84:87]
	v_mfma_f32_16x16x32_bf16 v[80:83], v[178:181], v[204:207], v[80:83]
	v_mfma_f32_16x16x32_bf16 v[68:71], v[170:173], v[212:215], v[68:71]
	v_mfma_f32_16x16x32_bf16 v[64:67], v[178:181], v[212:215], v[64:67]
	v_mfma_f32_16x16x32_bf16 v[116:119], v[174:177], v[192:195], v[116:119]
	v_mfma_f32_16x16x32_bf16 v[112:115], v[182:185], v[192:195], v[112:115]
	v_mfma_f32_16x16x32_bf16 v[100:103], v[174:177], v[200:203], v[100:103]
	v_mfma_f32_16x16x32_bf16 v[96:99], v[182:185], v[200:203], v[96:99]
	v_mfma_f32_16x16x32_bf16 v[84:87], v[174:177], v[208:211], v[84:87]
	v_mfma_f32_16x16x32_bf16 v[80:83], v[182:185], v[208:211], v[80:83]
	v_mfma_f32_16x16x32_bf16 v[68:71], v[174:177], v[216:219], v[68:71]
	v_mfma_f32_16x16x32_bf16 v[64:67], v[182:185], v[216:219], v[64:67]
	s_setprio 0
	s_barrier
	s_add_i32 s34, s51, s0
	s_mov_b32 m0, s34
	ds_read_b128 v[188:191], v155 offset:49152
	ds_read_b128 v[192:195], v155 offset:50176
	ds_read_b128 v[196:199], v155 offset:51200
	ds_read_b128 v[200:203], v155 offset:52224
	ds_read_b128 v[204:207], v155 offset:53248
	global_load_lds_dwordx4 v130, s[98:99]
	s_add_i32 m0, s34, 0x2000
	s_add_u32 s30, s30, 0x80080
	s_addc_u32 s31, s31, 0
	s_add_i32 s34, s54, s0
	global_load_lds_dwordx4 v134, s[98:99]
	s_mov_b32 m0, s34
	ds_read_b128 v[216:219], v155 offset:56320
	global_load_lds_dwordx4 v130, s[30:31]
	s_add_i32 m0, s34, 0x2000
	ds_read_b128 v[212:215], v155 offset:55296
	global_load_lds_dwordx4 v134, s[30:31]
	s_mov_b32 m0, s41
	ds_read_b128 v[208:211], v155 offset:54272
	global_load_lds_dwordx4 v128, s[100:101]
	v_lshl_add_u64 v[148:149], v[224:225], 0, s[14:15]
	s_mov_b32 m0, s42
	s_nop 0
	global_load_lds_dwordx4 v132, s[100:101]
	s_waitcnt vmcnt(8)
	s_waitcnt lgkmcnt(0)
	s_barrier
	s_setprio 1
	s_waitcnt lgkmcnt(0)
	v_mfma_f32_16x16x32_bf16 v[60:63], v[144:147], v[188:191], v[60:63]
	v_mfma_f32_16x16x32_bf16 v[56:59], v[162:165], v[188:191], v[56:59]
	v_mfma_f32_16x16x32_bf16 v[44:47], v[144:147], v[196:199], v[44:47]
	v_mfma_f32_16x16x32_bf16 v[40:43], v[162:165], v[196:199], v[40:43]
	v_mfma_f32_16x16x32_bf16 v[28:31], v[144:147], v[204:207], v[28:31]
	v_mfma_f32_16x16x32_bf16 v[24:27], v[162:165], v[204:207], v[24:27]
	v_mfma_f32_16x16x32_bf16 v[12:15], v[144:147], v[212:215], v[12:15]
	v_mfma_f32_16x16x32_bf16 v[8:11], v[162:165], v[212:215], v[8:11]
	v_mfma_f32_16x16x32_bf16 v[60:63], v[158:161], v[192:195], v[60:63]
	v_mfma_f32_16x16x32_bf16 v[56:59], v[166:169], v[192:195], v[56:59]
	v_mfma_f32_16x16x32_bf16 v[44:47], v[158:161], v[200:203], v[44:47]
	v_mfma_f32_16x16x32_bf16 v[40:43], v[166:169], v[200:203], v[40:43]
	v_mfma_f32_16x16x32_bf16 v[28:31], v[158:161], v[208:211], v[28:31]
	v_mfma_f32_16x16x32_bf16 v[24:27], v[166:169], v[208:211], v[24:27]
	v_mfma_f32_16x16x32_bf16 v[12:15], v[158:161], v[216:219], v[12:15]
	v_mfma_f32_16x16x32_bf16 v[8:11], v[166:169], v[216:219], v[8:11]
	v_mfma_f32_16x16x32_bf16 v[52:55], v[170:173], v[188:191], v[52:55]
	v_mfma_f32_16x16x32_bf16 v[48:51], v[178:181], v[188:191], v[48:51]
	v_mfma_f32_16x16x32_bf16 v[36:39], v[170:173], v[196:199], v[36:39]
	v_mfma_f32_16x16x32_bf16 v[32:35], v[178:181], v[196:199], v[32:35]
	v_mfma_f32_16x16x32_bf16 v[20:23], v[170:173], v[204:207], v[20:23]
	v_mfma_f32_16x16x32_bf16 v[16:19], v[178:181], v[204:207], v[16:19]
	v_mfma_f32_16x16x32_bf16 v[4:7], v[170:173], v[212:215], v[4:7]
	v_mfma_f32_16x16x32_bf16 v[0:3], v[178:181], v[212:215], v[0:3]
	v_mfma_f32_16x16x32_bf16 v[52:55], v[174:177], v[192:195], v[52:55]
	v_mfma_f32_16x16x32_bf16 v[48:51], v[182:185], v[192:195], v[48:51]
	v_mfma_f32_16x16x32_bf16 v[36:39], v[174:177], v[200:203], v[36:39]
	v_mfma_f32_16x16x32_bf16 v[32:35], v[182:185], v[200:203], v[32:35]
	v_mfma_f32_16x16x32_bf16 v[20:23], v[174:177], v[208:211], v[20:23]
	v_mfma_f32_16x16x32_bf16 v[16:19], v[182:185], v[208:211], v[16:19]
	v_mfma_f32_16x16x32_bf16 v[4:7], v[174:177], v[216:219], v[4:7]
	v_mfma_f32_16x16x32_bf16 v[0:3], v[182:185], v[216:219], v[0:3]
	s_setprio 0
	s_barrier
	s_add_i32 s50, s50, 2
	s_add_u32 s28, s28, 0x100
	s_addc_u32 s29, s29, 0
	s_add_u32 s48, s48, 0x100
	s_addc_u32 s49, s49, 0
	s_cmp_gt_u32 s50, 29
	s_cbranch_scc0 .LBB0_637
	s_and_b64 vcc, exec, s[16:17]
	s_cbranch_vccz .LBB0_640
	s_barrier

; #define PG8_STAGE(bufoff, gbase, voff) do { _Pragma("unroll") for (int _i = 0; _i < 2; ++_i) \
;         __builtin_amdgcn_global_load_lds((const unsigned*)((const char*)(gbase) + (voff)[_i]), (PG8_LAS unsigned*)(lds + (bufoff) + ldsw + _i * 8192), 16, 0, 0); } while (0)
; #define PG8_LDA(dst, b, h) do { _Pragma("unroll") for (int m = 0; m < 4; ++m) _Pragma("unroll") for (int k = 0; k < 2; ++k) dst[m][k] = *(const PG8_LAS bf16x8*)(lds + PG8_SA(b, h) + aoff + m * 2048 + k * 1024); } while (0)
; #define PG8_LDB(dst, b, h) do { _Pragma("unroll") for (int n = 0; n < 2; ++n) _Pragma("unroll") for (int k = 0; k < 2; ++k) dst[n][k] = *(const PG8_LAS bf16x8*)(lds + PG8_SB(b, h) + boff + n * 2048 + k * 1024); } while (0)
; #define PG8_MMA(ai, bj, At, Bt) do { __builtin_amdgcn_s_setprio(1); _Pragma("unroll") for (int m = 0; m < 4; ++m) _Pragma("unroll") for (int n = 0; n < 2; ++n) _Pragma("unroll") for (int k = 0; k < 2; ++k) \
;         acc[ai][bj][m][n] = __builtin_amdgcn_mfma_f32_16x16x32_bf16(Bt[n][k], At[m][k], acc[ai][bj][m][n], 0, 0, 0); __builtin_amdgcn_s_setprio(0); } while (0)
; #define PG8_WAIT_V(n) asm volatile("s_waitcnt vmcnt(" #n ")" ::: "memory")
; #define PG8_WAIT_L(n) asm volatile("s_waitcnt lgkmcnt(" #n ")" ::: "memory")
; template <class Epi, class Sched, bool ALIGN_EPI = false, bool SP2 = false>
; __device__ __forceinline__ void gemm_phase(PG8_LAS unsigned char* lds, const Gemm g, const Sched& S, const Epi& E) {
;     ...
;             const bool last = (t == nt - 2);
;             const char* a1 = cA + (size_t)(t + 1) * kstep;
;             const char* a2 = last ? nA : cA + (size_t)(t + 2) * kstep; const char* b2 = last ? nB : cB + (size_t)(t + 2) * kstep;
;             const char* a3 = a2 + kstep; const char* b3 = b2 + kstep;
;             if (last && has_next) S.a_ready(nxt);
;             if constexpr (SP2) {
;             PG8_LDB(B0, 0, 0); PG8_LDB(B1, 0, 1); PG8_SCHED; PG8_LDA(At, 0, 0); PG8_STAGE(PG8_SA(1, 1), a1 + hstep, voffA);
;             PG8_WAIT_V(8); PG8_WAIT_L(0); PG8_BAR; PG8_MMA(0, 0, At, B0); PG8_MMA(0, 1, At, B1); PG8_BAR; PG8_SCHED;
;             PG8_LDA(At, 0, 1); PG8_STAGE(PG8_SB(0, 0), b2, voffB); PG8_STAGE(PG8_SB(0, 1), b2 + hstep, voffB); PG8_STAGE(PG8_SA(0, 0), a2, voffA);
;             PG8_WAIT_V(8); PG8_WAIT_L(0); PG8_BAR; PG8_MMA(1, 0, At, B0); PG8_MMA(1, 1, At, B1); PG8_BAR; PG8_SCHED;
.LBB0_728:
	ds_read_b128 v[144:147], v151
	ds_read_b128 v[156:159], v151 offset:1024
	ds_read_b128 v[160:163], v151 offset:2048
	ds_read_b128 v[164:167], v151 offset:3072
	ds_read_b128 v[168:171], v152
	ds_read_b128 v[172:175], v152 offset:1024
	ds_read_b128 v[176:179], v152 offset:2048
	ds_read_b128 v[180:183], v152 offset:3072
	s_add_u32 s28, s26, 0xfff80080
	s_addc_u32 s29, s27, -1
	s_cmp_eq_u32 s51, 28
	s_cselect_b32 s31, s19, s29
	s_cselect_b32 s30, s47, s28
	s_cselect_b32 s29, s17, s50
	s_cselect_b32 s28, s48, s49
	s_add_i32 m0, s25, 0xc000
	ds_read_b128 v[188:191], v153
	ds_read_b128 v[192:195], v153 offset:1024
	ds_read_b128 v[196:199], v153 offset:2048
	ds_read_b128 v[200:203], v153 offset:3072
	ds_read_b128 v[204:207], v153 offset:4096
	ds_read_b128 v[208:211], v153 offset:5120
	ds_read_b128 v[212:215], v153 offset:6144
	global_load_lds_dwordx4 v136, s[26:27]
	s_add_i32 m0, s25, 0xe000
	ds_read_b128 v[216:219], v153 offset:7168
	global_load_lds_dwordx4 v138, s[26:27]
	s_waitcnt vmcnt(8)
	s_waitcnt lgkmcnt(0)
	s_barrier
	s_setprio 1
	s_waitcnt lgkmcnt(0)
	v_mfma_f32_16x16x32_bf16 v[124:127], v[144:147], v[188:191], v[124:127]
	v_mfma_f32_16x16x32_bf16 v[120:123], v[160:163], v[188:191], v[120:123]
	v_mfma_f32_16x16x32_bf16 v[108:111], v[144:147], v[196:199], v[108:111]
	v_mfma_f32_16x16x32_bf16 v[104:107], v[160:163], v[196:199], v[104:107]
	v_mfma_f32_16x16x32_bf16 v[92:95], v[144:147], v[204:207], v[92:95]
	v_mfma_f32_16x16x32_bf16 v[88:91], v[160:163], v[204:207], v[88:91]
	v_mfma_f32_16x16x32_bf16 v[76:79], v[144:147], v[212:215], v[76:79]
	v_mfma_f32_16x16x32_bf16 v[72:75], v[160:163], v[212:215], v[72:75]
	v_mfma_f32_16x16x32_bf16 v[124:127], v[156:159], v[192:195], v[124:127]
	v_mfma_f32_16x16x32_bf16 v[120:123], v[164:167], v[192:195], v[120:123]
	v_mfma_f32_16x16x32_bf16 v[108:111], v[156:159], v[200:203], v[108:111]
	v_mfma_f32_16x16x32_bf16 v[104:107], v[164:167], v[200:203], v[104:107]
	v_mfma_f32_16x16x32_bf16 v[92:95], v[156:159], v[208:211], v[92:95]
	v_mfma_f32_16x16x32_bf16 v[88:91], v[164:167], v[208:211], v[88:91]
	v_mfma_f32_16x16x32_bf16 v[76:79], v[156:159], v[216:219], v[76:79]
	v_mfma_f32_16x16x32_bf16 v[72:75], v[164:167], v[216:219], v[72:75]
	v_mfma_f32_16x16x32_bf16 v[116:119], v[168:171], v[188:191], v[116:119]
	v_mfma_f32_16x16x32_bf16 v[112:115], v[176:179], v[188:191], v[112:115]
	v_mfma_f32_16x16x32_bf16 v[100:103], v[168:171], v[196:199], v[100:103]
	v_mfma_f32_16x16x32_bf16 v[96:99], v[176:179], v[196:199], v[96:99]
	v_mfma_f32_16x16x32_bf16 v[84:87], v[168:171], v[204:207], v[84:87]
	v_mfma_f32_16x16x32_bf16 v[80:83], v[176:179], v[204:207], v[80:83]
	v_mfma_f32_16x16x32_bf16 v[68:71], v[168:171], v[212:215], v[68:71]
	v_mfma_f32_16x16x32_bf16 v[64:67], v[176:179], v[212:215], v[64:67]
	v_mfma_f32_16x16x32_bf16 v[116:119], v[172:175], v[192:195], v[116:119]
	v_mfma_f32_16x16x32_bf16 v[112:115], v[180:183], v[192:195], v[112:115]
	v_mfma_f32_16x16x32_bf16 v[100:103], v[172:175], v[200:203], v[100:103]
	v_mfma_f32_16x16x32_bf16 v[96:99], v[180:183], v[200:203], v[96:99]
	v_mfma_f32_16x16x32_bf16 v[84:87], v[172:175], v[208:211], v[84:87]
	v_mfma_f32_16x16x32_bf16 v[80:83], v[180:183], v[208:211], v[80:83]
	v_mfma_f32_16x16x32_bf16 v[68:71], v[172:175], v[216:219], v[68:71]
	v_mfma_f32_16x16x32_bf16 v[64:67], v[180:183], v[216:219], v[64:67]
	s_setprio 0
	s_barrier
	s_add_u32 s98, s28, s12
	s_addc_u32 s99, s29, s13
	s_add_u32 s100, s30, s12
	s_addc_u32 s101, s31, s13
	s_add_i32 s54, s43, s1
	s_mov_b32 m0, s54
	ds_read_b128 v[188:191], v153 offset:16384
	ds_read_b128 v[192:195], v153 offset:17408
	ds_read_b128 v[196:199], v153 offset:18432
	ds_read_b128 v[200:203], v153 offset:19456
	global_load_lds_dwordx4 v130, s[28:29]
	s_add_i32 m0, s54, 0x2000
	s_add_u32 s54, s28, 0x80000
	s_addc_u32 s55, s29, 0
	s_add_i32 s56, s44, s1
	global_load_lds_dwordx4 v134, s[28:29]
	s_mov_b32 m0, s56
	ds_read_b128 v[216:219], v153 offset:23552
	global_load_lds_dwordx4 v130, s[54:55]
	s_add_i32 m0, s56, 0x2000
	ds_read_b128 v[212:215], v153 offset:22528
	global_load_lds_dwordx4 v134, s[54:55]
	s_mov_b32 m0, s25
	ds_read_b128 v[208:211], v153 offset:21504
	global_load_lds_dwordx4 v128, s[30:31]
	s_mov_b32 m0, s34
	ds_read_b128 v[204:207], v153 offset:20480
	global_load_lds_dwordx4 v132, s[30:31]
	s_waitcnt vmcnt(8)
	s_waitcnt lgkmcnt(0)
	s_barrier
	s_setprio 1
	s_waitcnt lgkmcnt(0)
	v_mfma_f32_16x16x32_bf16 v[60:63], v[144:147], v[188:191], v[60:63]
	v_mfma_f32_16x16x32_bf16 v[56:59], v[160:163], v[188:191], v[56:59]
	v_mfma_f32_16x16x32_bf16 v[44:47], v[144:147], v[196:199], v[44:47]
	v_mfma_f32_16x16x32_bf16 v[40:43], v[160:163], v[196:199], v[40:43]
	v_mfma_f32_16x16x32_bf16 v[28:31], v[144:147], v[204:207], v[28:31]
	v_mfma_f32_16x16x32_bf16 v[24:27], v[160:163], v[204:207], v[24:27]
	v_mfma_f32_16x16x32_bf16 v[12:15], v[144:147], v[212:215], v[12:15]
	v_mfma_f32_16x16x32_bf16 v[8:11], v[160:163], v[212:215], v[8:11]
	v_mfma_f32_16x16x32_bf16 v[60:63], v[156:159], v[192:195], v[60:63]
	v_mfma_f32_16x16x32_bf16 v[56:59], v[164:167], v[192:195], v[56:59]
	v_mfma_f32_16x16x32_bf16 v[44:47], v[156:159], v[200:203], v[44:47]
	v_mfma_f32_16x16x32_bf16 v[40:43], v[164:167], v[200:203], v[40:43]
	v_mfma_f32_16x16x32_bf16 v[28:31], v[156:159], v[208:211], v[28:31]
	v_mfma_f32_16x16x32_bf16 v[24:27], v[164:167], v[208:211], v[24:27]
	v_mfma_f32_16x16x32_bf16 v[12:15], v[156:159], v[216:219], v[12:15]
	v_mfma_f32_16x16x32_bf16 v[8:11], v[164:167], v[216:219], v[8:11]
	v_mfma_f32_16x16x32_bf16 v[52:55], v[168:171], v[188:191], v[52:55]
	v_mfma_f32_16x16x32_bf16 v[48:51], v[176:179], v[188:191], v[48:51]
	v_mfma_f32_16x16x32_bf16 v[36:39], v[168:171], v[196:199], v[36:39]
	v_mfma_f32_16x16x32_bf16 v[32:35], v[176:179], v[196:199], v[32:35]
	v_mfma_f32_16x16x32_bf16 v[20:23], v[168:171], v[204:207], v[20:23]
	v_mfma_f32_16x16x32_bf16 v[16:19], v[176:179], v[204:207], v[16:19]
	v_mfma_f32_16x16x32_bf16 v[4:7], v[168:171], v[212:215], v[4:7]
	v_mfma_f32_16x16x32_bf16 v[0:3], v[176:179], v[212:215], v[0:3]
	v_mfma_f32_16x16x32_bf16 v[52:55], v[172:175], v[192:195], v[52:55]
	v_mfma_f32_16x16x32_bf16 v[48:51], v[180:183], v[192:195], v[48:51]
	v_mfma_f32_16x16x32_bf16 v[36:39], v[172:175], v[200:203], v[36:39]
	v_mfma_f32_16x16x32_bf16 v[32:35], v[180:183], v[200:203], v[32:35]
	v_mfma_f32_16x16x32_bf16 v[20:23], v[172:175], v[208:211], v[20:23]
	v_mfma_f32_16x16x32_bf16 v[16:19], v[180:183], v[208:211], v[16:19]
	v_mfma_f32_16x16x32_bf16 v[4:7], v[172:175], v[216:219], v[4:7]
	v_mfma_f32_16x16x32_bf16 v[0:3], v[180:183], v[216:219], v[0:3]
	s_setprio 0
	s_barrier
; #define PG8_STAGE(bufoff, gbase, voff) do { _Pragma("unroll") for (int _i = 0; _i < 2; ++_i) \
;         __builtin_amdgcn_global_load_lds((const unsigned*)((const char*)(gbase) + (voff)[_i]), (PG8_LAS unsigned*)(lds + (bufoff) + ldsw + _i * 8192), 16, 0, 0); } while (0)
; #define PG8_LDA(dst, b, h) do { _Pragma("unroll") for (int m = 0; m < 4; ++m) _Pragma("unroll") for (int k = 0; k < 2; ++k) dst[m][k] = *(const PG8_LAS bf16x8*)(lds + PG8_SA(b, h) + aoff + m * 2048 + k * 1024); } while (0)
; #define PG8_LDB(dst, b, h) do { _Pragma("unroll") for (int n = 0; n < 2; ++n) _Pragma("unroll") for (int k = 0; k < 2; ++k) dst[n][k] = *(const PG8_LAS bf16x8*)(lds + PG8_SB(b, h) + boff + n * 2048 + k * 1024); } while (0)
; #define PG8_MMA(ai, bj, At, Bt) do { __builtin_amdgcn_s_setprio(1); _Pragma("unroll") for (int m = 0; m < 4; ++m) _Pragma("unroll") for (int n = 0; n < 2; ++n) _Pragma("unroll") for (int k = 0; k < 2; ++k) \
;         acc[ai][bj][m][n] = __builtin_amdgcn_mfma_f32_16x16x32_bf16(Bt[n][k], At[m][k], acc[ai][bj][m][n], 0, 0, 0); __builtin_amdgcn_s_setprio(0); } while (0)
; #define PG8_WAIT_V(n) asm volatile("s_waitcnt vmcnt(" #n ")" ::: "memory")
; #define PG8_WAIT_L(n) asm volatile("s_waitcnt lgkmcnt(" #n ")" ::: "memory")
; #define PG8_BAR __builtin_amdgcn_s_barrier()
; #define PG8_SCHED __builtin_amdgcn_sched_barrier(0)
; template <class Epi, class Sched, bool ALIGN_EPI = false, bool SP2 = false>
; __device__ __forceinline__ void gemm_phase(PG8_LAS unsigned char* lds, const Gemm g, const Sched& S, const Epi& E) {
;     ...
;             PG8_LDB(B0, 1, 0); PG8_LDB(B1, 1, 1); PG8_SCHED; PG8_LDA(At, 1, 0); PG8_STAGE(PG8_SA(0, 1), a2 + hstep, voffA);
;             PG8_WAIT_V(8); PG8_WAIT_L(0); PG8_BAR; PG8_MMA(0, 0, At, B0); PG8_MMA(0, 1, At, B1); PG8_BAR; PG8_SCHED;
;             PG8_LDA(At, 1, 1); PG8_STAGE(PG8_SB(1, 0), b3, voffB); PG8_STAGE(PG8_SB(1, 1), b3 + hstep, voffB); PG8_STAGE(PG8_SA(1, 0), a3, voffA);
;             PG8_WAIT_V(8); PG8_WAIT_L(0); PG8_BAR; PG8_MMA(1, 0, At, B0); PG8_MMA(1, 1, At, B1); PG8_BAR; PG8_SCHED;
;     ...
;         if constexpr (ALIGN_EPI) { if (wr == 0) PG8_BAR; }
	s_add_i32 s54, 0, 0x18000
	v_add_u32_e32 v155, s54, v150
	s_add_i32 s55, 0, 0x1c000
	ds_read_b128 v[144:147], v155
	ds_read_b128 v[156:159], v155 offset:1024
	ds_read_b128 v[160:163], v155 offset:2048
	ds_read_b128 v[164:167], v155 offset:3072
	v_add_u32_e32 v155, s55, v150
	ds_read_b128 v[168:171], v155
	ds_read_b128 v[172:175], v155 offset:1024
	ds_read_b128 v[176:179], v155 offset:2048
	ds_read_b128 v[180:183], v155 offset:3072
	s_add_u32 s30, s30, 0x80000
	s_addc_u32 s31, s31, 0
	s_mov_b32 m0, s35
	ds_read_b128 v[188:191], v153 offset:32768
	ds_read_b128 v[192:195], v153 offset:33792
	ds_read_b128 v[196:199], v153 offset:34816
	ds_read_b128 v[200:203], v153 offset:35840
	ds_read_b128 v[204:207], v153 offset:36864
	ds_read_b128 v[208:211], v153 offset:37888
	ds_read_b128 v[212:215], v153 offset:38912
	global_load_lds_dwordx4 v128, s[30:31]
	s_mov_b32 m0, s36
	ds_read_b128 v[216:219], v153 offset:39936
	global_load_lds_dwordx4 v132, s[30:31]
	s_waitcnt vmcnt(8)
	s_waitcnt lgkmcnt(0)
	s_barrier
	s_setprio 1
	s_waitcnt lgkmcnt(0)
	v_mfma_f32_16x16x32_bf16 v[124:127], v[144:147], v[188:191], v[124:127]
	v_mfma_f32_16x16x32_bf16 v[120:123], v[160:163], v[188:191], v[120:123]
	v_mfma_f32_16x16x32_bf16 v[108:111], v[144:147], v[196:199], v[108:111]
	v_mfma_f32_16x16x32_bf16 v[104:107], v[160:163], v[196:199], v[104:107]
	v_mfma_f32_16x16x32_bf16 v[92:95], v[144:147], v[204:207], v[92:95]
	v_mfma_f32_16x16x32_bf16 v[88:91], v[160:163], v[204:207], v[88:91]
	v_mfma_f32_16x16x32_bf16 v[76:79], v[144:147], v[212:215], v[76:79]
	v_mfma_f32_16x16x32_bf16 v[72:75], v[160:163], v[212:215], v[72:75]
	v_mfma_f32_16x16x32_bf16 v[124:127], v[156:159], v[192:195], v[124:127]
	v_mfma_f32_16x16x32_bf16 v[120:123], v[164:167], v[192:195], v[120:123]
	v_mfma_f32_16x16x32_bf16 v[108:111], v[156:159], v[200:203], v[108:111]
	v_mfma_f32_16x16x32_bf16 v[104:107], v[164:167], v[200:203], v[104:107]
	v_mfma_f32_16x16x32_bf16 v[92:95], v[156:159], v[208:211], v[92:95]
	v_mfma_f32_16x16x32_bf16 v[88:91], v[164:167], v[208:211], v[88:91]
	v_mfma_f32_16x16x32_bf16 v[76:79], v[156:159], v[216:219], v[76:79]
	v_mfma_f32_16x16x32_bf16 v[72:75], v[164:167], v[216:219], v[72:75]
	v_mfma_f32_16x16x32_bf16 v[116:119], v[168:171], v[188:191], v[116:119]
	v_mfma_f32_16x16x32_bf16 v[112:115], v[176:179], v[188:191], v[112:115]
	v_mfma_f32_16x16x32_bf16 v[100:103], v[168:171], v[196:199], v[100:103]
	v_mfma_f32_16x16x32_bf16 v[96:99], v[176:179], v[196:199], v[96:99]
	v_mfma_f32_16x16x32_bf16 v[84:87], v[168:171], v[204:207], v[84:87]
	v_mfma_f32_16x16x32_bf16 v[80:83], v[176:179], v[204:207], v[80:83]
	v_mfma_f32_16x16x32_bf16 v[68:71], v[168:171], v[212:215], v[68:71]
	v_mfma_f32_16x16x32_bf16 v[64:67], v[176:179], v[212:215], v[64:67]
	v_mfma_f32_16x16x32_bf16 v[116:119], v[172:175], v[192:195], v[116:119]
	v_mfma_f32_16x16x32_bf16 v[112:115], v[180:183], v[192:195], v[112:115]
	v_mfma_f32_16x16x32_bf16 v[100:103], v[172:175], v[200:203], v[100:103]
	v_mfma_f32_16x16x32_bf16 v[96:99], v[180:183], v[200:203], v[96:99]
	v_mfma_f32_16x16x32_bf16 v[84:87], v[172:175], v[208:211], v[84:87]
	v_mfma_f32_16x16x32_bf16 v[80:83], v[180:183], v[208:211], v[80:83]
	v_mfma_f32_16x16x32_bf16 v[68:71], v[172:175], v[216:219], v[68:71]
	v_mfma_f32_16x16x32_bf16 v[64:67], v[180:183], v[216:219], v[64:67]
	s_setprio 0
	s_barrier
	s_add_i32 s30, s54, s1
	s_mov_b32 m0, s30
	ds_read_b128 v[188:191], v153 offset:49152
	ds_read_b128 v[192:195], v153 offset:50176
	ds_read_b128 v[196:199], v153 offset:51200
	ds_read_b128 v[200:203], v153 offset:52224
	global_load_lds_dwordx4 v130, s[98:99]
	s_add_i32 m0, s30, 0x2000
	s_add_u32 s28, s28, 0x80080
	s_addc_u32 s29, s29, 0
	s_add_i32 s30, s55, s1
	global_load_lds_dwordx4 v134, s[98:99]
	s_mov_b32 m0, s30
	ds_read_b128 v[216:219], v153 offset:56320
	global_load_lds_dwordx4 v130, s[28:29]
	s_add_i32 m0, s30, 0x2000
	ds_read_b128 v[212:215], v153 offset:55296
	global_load_lds_dwordx4 v134, s[28:29]
	s_mov_b32 m0, s40
	ds_read_b128 v[208:211], v153 offset:54272
	global_load_lds_dwordx4 v128, s[100:101]
	s_mov_b32 m0, s41
	ds_read_b128 v[204:207], v153 offset:53248
	global_load_lds_dwordx4 v132, s[100:101]
	s_waitcnt vmcnt(8)
	s_waitcnt lgkmcnt(0)
	s_barrier
	s_setprio 1
	s_waitcnt lgkmcnt(0)
	v_mfma_f32_16x16x32_bf16 v[60:63], v[144:147], v[188:191], v[60:63]
	v_mfma_f32_16x16x32_bf16 v[56:59], v[160:163], v[188:191], v[56:59]
	v_mfma_f32_16x16x32_bf16 v[44:47], v[144:147], v[196:199], v[44:47]
	v_mfma_f32_16x16x32_bf16 v[40:43], v[160:163], v[196:199], v[40:43]
	v_mfma_f32_16x16x32_bf16 v[28:31], v[144:147], v[204:207], v[28:31]
	v_mfma_f32_16x16x32_bf16 v[24:27], v[160:163], v[204:207], v[24:27]
	v_mfma_f32_16x16x32_bf16 v[12:15], v[144:147], v[212:215], v[12:15]
	v_mfma_f32_16x16x32_bf16 v[8:11], v[160:163], v[212:215], v[8:11]
	v_mfma_f32_16x16x32_bf16 v[60:63], v[156:159], v[192:195], v[60:63]
	v_mfma_f32_16x16x32_bf16 v[56:59], v[164:167], v[192:195], v[56:59]
	v_mfma_f32_16x16x32_bf16 v[44:47], v[156:159], v[200:203], v[44:47]
	v_mfma_f32_16x16x32_bf16 v[40:43], v[164:167], v[200:203], v[40:43]
	v_mfma_f32_16x16x32_bf16 v[28:31], v[156:159], v[208:211], v[28:31]
	v_mfma_f32_16x16x32_bf16 v[24:27], v[164:167], v[208:211], v[24:27]
	v_mfma_f32_16x16x32_bf16 v[12:15], v[156:159], v[216:219], v[12:15]
	v_mfma_f32_16x16x32_bf16 v[8:11], v[164:167], v[216:219], v[8:11]
	v_mfma_f32_16x16x32_bf16 v[52:55], v[168:171], v[188:191], v[52:55]
	v_mfma_f32_16x16x32_bf16 v[48:51], v[176:179], v[188:191], v[48:51]
	v_mfma_f32_16x16x32_bf16 v[36:39], v[168:171], v[196:199], v[36:39]
	v_mfma_f32_16x16x32_bf16 v[32:35], v[176:179], v[196:199], v[32:35]
	v_mfma_f32_16x16x32_bf16 v[20:23], v[168:171], v[204:207], v[20:23]
	v_mfma_f32_16x16x32_bf16 v[16:19], v[176:179], v[204:207], v[16:19]
	v_mfma_f32_16x16x32_bf16 v[4:7], v[168:171], v[212:215], v[4:7]
	v_mfma_f32_16x16x32_bf16 v[0:3], v[176:179], v[212:215], v[0:3]
	v_mfma_f32_16x16x32_bf16 v[52:55], v[172:175], v[192:195], v[52:55]
	v_mfma_f32_16x16x32_bf16 v[48:51], v[180:183], v[192:195], v[48:51]
	v_mfma_f32_16x16x32_bf16 v[36:39], v[172:175], v[200:203], v[36:39]
	v_mfma_f32_16x16x32_bf16 v[32:35], v[180:183], v[200:203], v[32:35]
	v_mfma_f32_16x16x32_bf16 v[20:23], v[172:175], v[208:211], v[20:23]
	v_mfma_f32_16x16x32_bf16 v[16:19], v[180:183], v[208:211], v[16:19]
	v_mfma_f32_16x16x32_bf16 v[4:7], v[172:175], v[216:219], v[4:7]
	v_mfma_f32_16x16x32_bf16 v[0:3], v[180:183], v[216:219], v[0:3]
	s_setprio 0
	s_barrier
	s_add_i32 s51, s51, 2
	s_add_u32 s26, s26, 0x100
	s_addc_u32 s27, s27, 0
	s_add_u32 s49, s49, 0x100
	s_addc_u32 s50, s50, 0
	s_cmp_gt_u32 s51, 29
	s_cbranch_scc0 .LBB0_728
	s_and_b64 vcc, exec, s[14:15]
	s_cbranch_vccz .LBB0_731
	s_barrier

; #define PG8_STAGE(bufoff, gbase, voff) do { _Pragma("unroll") for (int _i = 0; _i < 2; ++_i) \
;         __builtin_amdgcn_global_load_lds((const unsigned*)((const char*)(gbase) + (voff)[_i]), (PG8_LAS unsigned*)(lds + (bufoff) + ldsw + _i * 8192), 16, 0, 0); } while (0)
; #define PG8_LDA(dst, b, h) do { _Pragma("unroll") for (int m = 0; m < 4; ++m) _Pragma("unroll") for (int k = 0; k < 2; ++k) dst[m][k] = *(const PG8_LAS bf16x8*)(lds + PG8_SA(b, h) + aoff + m * 2048 + k * 1024); } while (0)
; #define PG8_LDB(dst, b, h) do { _Pragma("unroll") for (int n = 0; n < 2; ++n) _Pragma("unroll") for (int k = 0; k < 2; ++k) dst[n][k] = *(const PG8_LAS bf16x8*)(lds + PG8_SB(b, h) + boff + n * 2048 + k * 1024); } while (0)
; #define PG8_MMA(ai, bj, At, Bt) do { __builtin_amdgcn_s_setprio(1); _Pragma("unroll") for (int m = 0; m < 4; ++m) _Pragma("unroll") for (int n = 0; n < 2; ++n) _Pragma("unroll") for (int k = 0; k < 2; ++k) \
;         acc[ai][bj][m][n] = __builtin_amdgcn_mfma_f32_16x16x32_bf16(Bt[n][k], At[m][k], acc[ai][bj][m][n], 0, 0, 0); __builtin_amdgcn_s_setprio(0); } while (0)
; #define PG8_WAIT_V(n) asm volatile("s_waitcnt vmcnt(" #n ")" ::: "memory")
; #define PG8_WAIT_L(n) asm volatile("s_waitcnt lgkmcnt(" #n ")" ::: "memory")
; template <class Epi, class Sched, bool ALIGN_EPI = false, bool SP2 = false>
; __device__ __forceinline__ void gemm_phase(PG8_LAS unsigned char* lds, const Gemm g, const Sched& S, const Epi& E) {
;     ...
;             const bool last = (t == nt - 2);
;             const char* a1 = cA + (size_t)(t + 1) * kstep;
;             const char* a2 = last ? nA : cA + (size_t)(t + 2) * kstep; const char* b2 = last ? nB : cB + (size_t)(t + 2) * kstep;
;             const char* a3 = a2 + kstep; const char* b3 = b2 + kstep;
;             if (last && has_next) S.a_ready(nxt);
;             if constexpr (SP2) {
;             PG8_LDB(B0, 0, 0); PG8_LDB(B1, 0, 1); PG8_SCHED; PG8_LDA(At, 0, 0); PG8_STAGE(PG8_SA(1, 1), a1 + hstep, voffA);
;             PG8_WAIT_V(8); PG8_WAIT_L(0); PG8_BAR; PG8_MMA(0, 0, At, B0); PG8_MMA(0, 1, At, B1); PG8_BAR; PG8_SCHED;
;             PG8_LDA(At, 0, 1); PG8_STAGE(PG8_SB(0, 0), b2, voffB); PG8_STAGE(PG8_SB(0, 1), b2 + hstep, voffB); PG8_STAGE(PG8_SA(0, 0), a2, voffA);
;             PG8_WAIT_V(8); PG8_WAIT_L(0); PG8_BAR; PG8_MMA(1, 0, At, B0); PG8_MMA(1, 1, At, B1); PG8_BAR; PG8_SCHED;
.LBB0_803:
	ds_read_b128 v[144:147], v151
	ds_read_b128 v[154:157], v151 offset:1024
	ds_read_b128 v[158:161], v151 offset:2048
	ds_read_b128 v[162:165], v151 offset:3072
	ds_read_b128 v[166:169], v152
	ds_read_b128 v[170:173], v152 offset:1024
	ds_read_b128 v[174:177], v152 offset:2048
	ds_read_b128 v[178:181], v152 offset:3072
	s_add_u32 s30, s28, 0xffe00080
	s_addc_u32 s31, s29, -1
	s_cmpk_eq_i32 s51, 0x7c
	s_cselect_b32 s35, s21, s31
	s_cselect_b32 s34, s47, s30
	s_cselect_b32 s31, s19, s50
	s_cselect_b32 s30, s48, s49
	s_add_i32 m0, s27, 0xc000
	ds_read_b128 v[182:185], v153
	ds_read_b128 v[188:191], v153 offset:1024
	ds_read_b128 v[192:195], v153 offset:2048
	ds_read_b128 v[196:199], v153 offset:3072
	ds_read_b128 v[200:203], v153 offset:4096
	ds_read_b128 v[204:207], v153 offset:5120
	ds_read_b128 v[208:211], v153 offset:6144
	global_load_lds_dwordx4 v136, s[28:29]
	s_add_i32 m0, s27, 0xe000
	ds_read_b128 v[212:215], v153 offset:7168
	global_load_lds_dwordx4 v138, s[28:29]
	s_waitcnt vmcnt(8)
	s_waitcnt lgkmcnt(0)
	s_barrier
	s_setprio 1
	s_waitcnt lgkmcnt(0)
	v_mfma_f32_16x16x32_bf16 v[124:127], v[144:147], v[182:185], v[124:127]
	v_mfma_f32_16x16x32_bf16 v[120:123], v[158:161], v[182:185], v[120:123]
	v_mfma_f32_16x16x32_bf16 v[112:115], v[144:147], v[192:195], v[112:115]
	v_mfma_f32_16x16x32_bf16 v[104:107], v[158:161], v[192:195], v[104:107]
	v_mfma_f32_16x16x32_bf16 v[96:99], v[144:147], v[200:203], v[96:99]
	v_mfma_f32_16x16x32_bf16 v[88:91], v[158:161], v[200:203], v[88:91]
	v_mfma_f32_16x16x32_bf16 v[80:83], v[144:147], v[208:211], v[80:83]
	v_mfma_f32_16x16x32_bf16 v[72:75], v[158:161], v[208:211], v[72:75]
	v_mfma_f32_16x16x32_bf16 v[124:127], v[154:157], v[188:191], v[124:127]
	v_mfma_f32_16x16x32_bf16 v[120:123], v[162:165], v[188:191], v[120:123]
	v_mfma_f32_16x16x32_bf16 v[112:115], v[154:157], v[196:199], v[112:115]
	v_mfma_f32_16x16x32_bf16 v[104:107], v[162:165], v[196:199], v[104:107]
	v_mfma_f32_16x16x32_bf16 v[96:99], v[154:157], v[204:207], v[96:99]
	v_mfma_f32_16x16x32_bf16 v[88:91], v[162:165], v[204:207], v[88:91]
	v_mfma_f32_16x16x32_bf16 v[80:83], v[154:157], v[212:215], v[80:83]
	v_mfma_f32_16x16x32_bf16 v[72:75], v[162:165], v[212:215], v[72:75]
	v_mfma_f32_16x16x32_bf16 v[116:119], v[166:169], v[182:185], v[116:119]
	v_mfma_f32_16x16x32_bf16 v[108:111], v[174:177], v[182:185], v[108:111]
	v_mfma_f32_16x16x32_bf16 v[100:103], v[166:169], v[192:195], v[100:103]
	v_mfma_f32_16x16x32_bf16 v[92:95], v[174:177], v[192:195], v[92:95]
	v_mfma_f32_16x16x32_bf16 v[84:87], v[166:169], v[200:203], v[84:87]
	v_mfma_f32_16x16x32_bf16 v[76:79], v[174:177], v[200:203], v[76:79]
	v_mfma_f32_16x16x32_bf16 v[68:71], v[166:169], v[208:211], v[68:71]
	v_mfma_f32_16x16x32_bf16 v[64:67], v[174:177], v[208:211], v[64:67]
	v_mfma_f32_16x16x32_bf16 v[116:119], v[170:173], v[188:191], v[116:119]
	v_mfma_f32_16x16x32_bf16 v[108:111], v[178:181], v[188:191], v[108:111]
	v_mfma_f32_16x16x32_bf16 v[100:103], v[170:173], v[196:199], v[100:103]
	v_mfma_f32_16x16x32_bf16 v[92:95], v[178:181], v[196:199], v[92:95]
	v_mfma_f32_16x16x32_bf16 v[84:87], v[170:173], v[204:207], v[84:87]
	v_mfma_f32_16x16x32_bf16 v[76:79], v[178:181], v[204:207], v[76:79]
	v_mfma_f32_16x16x32_bf16 v[68:71], v[170:173], v[212:215], v[68:71]
	v_mfma_f32_16x16x32_bf16 v[64:67], v[178:181], v[212:215], v[64:67]
	s_setprio 0
	s_barrier
	s_add_u32 s98, s30, s14
	s_addc_u32 s99, s31, s15
	s_add_u32 s100, s34, s14
	s_addc_u32 s101, s35, s15
	s_add_i32 s54, s43, s1
	s_mov_b32 m0, s54
	ds_read_b128 v[182:185], v153 offset:16384
	ds_read_b128 v[188:191], v153 offset:17408
	ds_read_b128 v[192:195], v153 offset:18432
	ds_read_b128 v[196:199], v153 offset:19456
	global_load_lds_dwordx4 v130, s[30:31]
	s_add_i32 m0, s54, 0x2000
	s_add_u32 s54, s30, 0x200000
	s_addc_u32 s55, s31, 0
	s_add_i32 s56, s44, s1
	global_load_lds_dwordx4 v134, s[30:31]
	s_mov_b32 m0, s56
	ds_read_b128 v[212:215], v153 offset:23552
	global_load_lds_dwordx4 v130, s[54:55]
	s_add_i32 m0, s56, 0x2000
	ds_read_b128 v[208:211], v153 offset:22528
	global_load_lds_dwordx4 v134, s[54:55]
	s_mov_b32 m0, s27
	ds_read_b128 v[204:207], v153 offset:21504
	global_load_lds_dwordx4 v128, s[34:35]
	s_mov_b32 m0, s36
	ds_read_b128 v[200:203], v153 offset:20480
	global_load_lds_dwordx4 v132, s[34:35]
	s_waitcnt vmcnt(8)
	s_waitcnt lgkmcnt(0)
	s_barrier
	s_setprio 1
	s_waitcnt lgkmcnt(0)
	v_mfma_f32_16x16x32_bf16 v[60:63], v[144:147], v[182:185], v[60:63]
	v_mfma_f32_16x16x32_bf16 v[56:59], v[158:161], v[182:185], v[56:59]
	v_mfma_f32_16x16x32_bf16 v[48:51], v[144:147], v[192:195], v[48:51]
	v_mfma_f32_16x16x32_bf16 v[40:43], v[158:161], v[192:195], v[40:43]
	v_mfma_f32_16x16x32_bf16 v[32:35], v[144:147], v[200:203], v[32:35]
	v_mfma_f32_16x16x32_bf16 v[24:27], v[158:161], v[200:203], v[24:27]
	v_mfma_f32_16x16x32_bf16 v[16:19], v[144:147], v[208:211], v[16:19]
	v_mfma_f32_16x16x32_bf16 v[8:11], v[158:161], v[208:211], v[8:11]
	v_mfma_f32_16x16x32_bf16 v[60:63], v[154:157], v[188:191], v[60:63]
	v_mfma_f32_16x16x32_bf16 v[56:59], v[162:165], v[188:191], v[56:59]
	v_mfma_f32_16x16x32_bf16 v[48:51], v[154:157], v[196:199], v[48:51]
	v_mfma_f32_16x16x32_bf16 v[40:43], v[162:165], v[196:199], v[40:43]
	v_mfma_f32_16x16x32_bf16 v[32:35], v[154:157], v[204:207], v[32:35]
	v_mfma_f32_16x16x32_bf16 v[24:27], v[162:165], v[204:207], v[24:27]
	v_mfma_f32_16x16x32_bf16 v[16:19], v[154:157], v[212:215], v[16:19]
	v_mfma_f32_16x16x32_bf16 v[8:11], v[162:165], v[212:215], v[8:11]
	v_mfma_f32_16x16x32_bf16 v[52:55], v[166:169], v[182:185], v[52:55]
	v_mfma_f32_16x16x32_bf16 v[44:47], v[174:177], v[182:185], v[44:47]
	v_mfma_f32_16x16x32_bf16 v[36:39], v[166:169], v[192:195], v[36:39]
	v_mfma_f32_16x16x32_bf16 v[28:31], v[174:177], v[192:195], v[28:31]
	v_mfma_f32_16x16x32_bf16 v[20:23], v[166:169], v[200:203], v[20:23]
	v_mfma_f32_16x16x32_bf16 v[12:15], v[174:177], v[200:203], v[12:15]
	v_mfma_f32_16x16x32_bf16 v[4:7], v[166:169], v[208:211], v[4:7]
	v_mfma_f32_16x16x32_bf16 v[0:3], v[174:177], v[208:211], v[0:3]
	v_mfma_f32_16x16x32_bf16 v[52:55], v[170:173], v[188:191], v[52:55]
	v_mfma_f32_16x16x32_bf16 v[44:47], v[178:181], v[188:191], v[44:47]
	v_mfma_f32_16x16x32_bf16 v[36:39], v[170:173], v[196:199], v[36:39]
	v_mfma_f32_16x16x32_bf16 v[28:31], v[178:181], v[196:199], v[28:31]
	v_mfma_f32_16x16x32_bf16 v[20:23], v[170:173], v[204:207], v[20:23]
	v_mfma_f32_16x16x32_bf16 v[12:15], v[178:181], v[204:207], v[12:15]
	v_mfma_f32_16x16x32_bf16 v[4:7], v[170:173], v[212:215], v[4:7]
	v_mfma_f32_16x16x32_bf16 v[0:3], v[178:181], v[212:215], v[0:3]
	s_setprio 0
	s_barrier
; #define PG8_STAGE(bufoff, gbase, voff) do { _Pragma("unroll") for (int _i = 0; _i < 2; ++_i) \
;         __builtin_amdgcn_global_load_lds((const unsigned*)((const char*)(gbase) + (voff)[_i]), (PG8_LAS unsigned*)(lds + (bufoff) + ldsw + _i * 8192), 16, 0, 0); } while (0)
; #define PG8_LDA(dst, b, h) do { _Pragma("unroll") for (int m = 0; m < 4; ++m) _Pragma("unroll") for (int k = 0; k < 2; ++k) dst[m][k] = *(const PG8_LAS bf16x8*)(lds + PG8_SA(b, h) + aoff + m * 2048 + k * 1024); } while (0)
; #define PG8_LDB(dst, b, h) do { _Pragma("unroll") for (int n = 0; n < 2; ++n) _Pragma("unroll") for (int k = 0; k < 2; ++k) dst[n][k] = *(const PG8_LAS bf16x8*)(lds + PG8_SB(b, h) + boff + n * 2048 + k * 1024); } while (0)
; #define PG8_MMA(ai, bj, At, Bt) do { __builtin_amdgcn_s_setprio(1); _Pragma("unroll") for (int m = 0; m < 4; ++m) _Pragma("unroll") for (int n = 0; n < 2; ++n) _Pragma("unroll") for (int k = 0; k < 2; ++k) \
;         acc[ai][bj][m][n] = __builtin_amdgcn_mfma_f32_16x16x32_bf16(Bt[n][k], At[m][k], acc[ai][bj][m][n], 0, 0, 0); __builtin_amdgcn_s_setprio(0); } while (0)
; #define PG8_WAIT_V(n) asm volatile("s_waitcnt vmcnt(" #n ")" ::: "memory")
; #define PG8_WAIT_L(n) asm volatile("s_waitcnt lgkmcnt(" #n ")" ::: "memory")
; #define PG8_BAR __builtin_amdgcn_s_barrier()
; #define PG8_SCHED __builtin_amdgcn_sched_barrier(0)
; template <class Epi, class Sched, bool ALIGN_EPI = false, bool SP2 = false>
; __device__ __forceinline__ void gemm_phase(PG8_LAS unsigned char* lds, const Gemm g, const Sched& S, const Epi& E) {
;     ...
;             PG8_LDB(B0, 1, 0); PG8_LDB(B1, 1, 1); PG8_SCHED; PG8_LDA(At, 1, 0); PG8_STAGE(PG8_SA(0, 1), a2 + hstep, voffA);
;             PG8_WAIT_V(8); PG8_WAIT_L(0); PG8_BAR; PG8_MMA(0, 0, At, B0); PG8_MMA(0, 1, At, B1); PG8_BAR; PG8_SCHED;
;             PG8_LDA(At, 1, 1); PG8_STAGE(PG8_SB(1, 0), b3, voffB); PG8_STAGE(PG8_SB(1, 1), b3 + hstep, voffB); PG8_STAGE(PG8_SA(1, 0), a3, voffA);
;             PG8_WAIT_V(8); PG8_WAIT_L(0); PG8_BAR; PG8_MMA(1, 0, At, B0); PG8_MMA(1, 1, At, B1); PG8_BAR; PG8_SCHED;
;     ...
;         if constexpr (ALIGN_EPI) { if (wr == 0) PG8_BAR; }
	s_add_i32 s54, 0, 0x18000
	s_add_i32 s55, 0, 0x1c000
	v_add_u32_e32 v162, s54, v150
	v_add_u32_e32 v178, s55, v150
	ds_read_b128 v[144:147], v162
	ds_read_b128 v[154:157], v162 offset:1024
	ds_read_b128 v[158:161], v162 offset:2048
	ds_read_b128 v[162:165], v162 offset:3072
	ds_read_b128 v[166:169], v178
	ds_read_b128 v[170:173], v178 offset:1024
	ds_read_b128 v[174:177], v178 offset:2048
	ds_read_b128 v[178:181], v178 offset:3072
	s_add_u32 s34, s34, 0x200000
	s_addc_u32 s35, s35, 0
	s_mov_b32 m0, s37
	ds_read_b128 v[182:185], v153 offset:32768
	ds_read_b128 v[188:191], v153 offset:33792
	ds_read_b128 v[192:195], v153 offset:34816
	ds_read_b128 v[196:199], v153 offset:35840
	ds_read_b128 v[200:203], v153 offset:36864
	ds_read_b128 v[204:207], v153 offset:37888
	ds_read_b128 v[208:211], v153 offset:38912
	global_load_lds_dwordx4 v128, s[34:35]
	s_mov_b32 m0, s38
	ds_read_b128 v[212:215], v153 offset:39936
	global_load_lds_dwordx4 v132, s[34:35]
	s_waitcnt vmcnt(8)
	s_waitcnt lgkmcnt(0)
	s_barrier
	s_setprio 1
	s_waitcnt lgkmcnt(0)
	v_mfma_f32_16x16x32_bf16 v[124:127], v[144:147], v[182:185], v[124:127]
	v_mfma_f32_16x16x32_bf16 v[120:123], v[158:161], v[182:185], v[120:123]
	v_mfma_f32_16x16x32_bf16 v[112:115], v[144:147], v[192:195], v[112:115]
	v_mfma_f32_16x16x32_bf16 v[104:107], v[158:161], v[192:195], v[104:107]
	v_mfma_f32_16x16x32_bf16 v[96:99], v[144:147], v[200:203], v[96:99]
	v_mfma_f32_16x16x32_bf16 v[88:91], v[158:161], v[200:203], v[88:91]
	v_mfma_f32_16x16x32_bf16 v[80:83], v[144:147], v[208:211], v[80:83]
	v_mfma_f32_16x16x32_bf16 v[72:75], v[158:161], v[208:211], v[72:75]
	v_mfma_f32_16x16x32_bf16 v[124:127], v[154:157], v[188:191], v[124:127]
	v_mfma_f32_16x16x32_bf16 v[120:123], v[162:165], v[188:191], v[120:123]
	v_mfma_f32_16x16x32_bf16 v[112:115], v[154:157], v[196:199], v[112:115]
	v_mfma_f32_16x16x32_bf16 v[104:107], v[162:165], v[196:199], v[104:107]
	v_mfma_f32_16x16x32_bf16 v[96:99], v[154:157], v[204:207], v[96:99]
	v_mfma_f32_16x16x32_bf16 v[88:91], v[162:165], v[204:207], v[88:91]
	v_mfma_f32_16x16x32_bf16 v[80:83], v[154:157], v[212:215], v[80:83]
	v_mfma_f32_16x16x32_bf16 v[72:75], v[162:165], v[212:215], v[72:75]
	v_mfma_f32_16x16x32_bf16 v[116:119], v[166:169], v[182:185], v[116:119]
	v_mfma_f32_16x16x32_bf16 v[108:111], v[174:177], v[182:185], v[108:111]
	v_mfma_f32_16x16x32_bf16 v[100:103], v[166:169], v[192:195], v[100:103]
	v_mfma_f32_16x16x32_bf16 v[92:95], v[174:177], v[192:195], v[92:95]
	v_mfma_f32_16x16x32_bf16 v[84:87], v[166:169], v[200:203], v[84:87]
	v_mfma_f32_16x16x32_bf16 v[76:79], v[174:177], v[200:203], v[76:79]
	v_mfma_f32_16x16x32_bf16 v[68:71], v[166:169], v[208:211], v[68:71]
	v_mfma_f32_16x16x32_bf16 v[64:67], v[174:177], v[208:211], v[64:67]
	v_mfma_f32_16x16x32_bf16 v[116:119], v[170:173], v[188:191], v[116:119]
	v_mfma_f32_16x16x32_bf16 v[108:111], v[178:181], v[188:191], v[108:111]
	v_mfma_f32_16x16x32_bf16 v[100:103], v[170:173], v[196:199], v[100:103]
	v_mfma_f32_16x16x32_bf16 v[92:95], v[178:181], v[196:199], v[92:95]
	v_mfma_f32_16x16x32_bf16 v[84:87], v[170:173], v[204:207], v[84:87]
	v_mfma_f32_16x16x32_bf16 v[76:79], v[178:181], v[204:207], v[76:79]
	v_mfma_f32_16x16x32_bf16 v[68:71], v[170:173], v[212:215], v[68:71]
	v_mfma_f32_16x16x32_bf16 v[64:67], v[178:181], v[212:215], v[64:67]
	s_setprio 0
	s_barrier
	s_add_i32 s34, s54, s1
	s_mov_b32 m0, s34
	ds_read_b128 v[182:185], v153 offset:49152
	ds_read_b128 v[188:191], v153 offset:50176
	ds_read_b128 v[192:195], v153 offset:51200
	ds_read_b128 v[196:199], v153 offset:52224
	global_load_lds_dwordx4 v130, s[98:99]
	s_add_i32 m0, s34, 0x2000
	s_add_u32 s30, s30, 0x200080
	s_addc_u32 s31, s31, 0
	s_add_i32 s34, s55, s1
	global_load_lds_dwordx4 v134, s[98:99]
	s_mov_b32 m0, s34
	ds_read_b128 v[212:215], v153 offset:56320
	global_load_lds_dwordx4 v130, s[30:31]
	s_add_i32 m0, s34, 0x2000
	ds_read_b128 v[208:211], v153 offset:55296
	global_load_lds_dwordx4 v134, s[30:31]
	s_mov_b32 m0, s40
	ds_read_b128 v[204:207], v153 offset:54272
	global_load_lds_dwordx4 v128, s[100:101]
	s_mov_b32 m0, s41
	ds_read_b128 v[200:203], v153 offset:53248
	global_load_lds_dwordx4 v132, s[100:101]
	s_waitcnt vmcnt(8)
	s_waitcnt lgkmcnt(0)
	s_barrier
	s_setprio 1
	s_waitcnt lgkmcnt(0)
	v_mfma_f32_16x16x32_bf16 v[60:63], v[144:147], v[182:185], v[60:63]
	v_mfma_f32_16x16x32_bf16 v[56:59], v[158:161], v[182:185], v[56:59]
	v_mfma_f32_16x16x32_bf16 v[48:51], v[144:147], v[192:195], v[48:51]
	v_mfma_f32_16x16x32_bf16 v[40:43], v[158:161], v[192:195], v[40:43]
	v_mfma_f32_16x16x32_bf16 v[32:35], v[144:147], v[200:203], v[32:35]
	v_mfma_f32_16x16x32_bf16 v[24:27], v[158:161], v[200:203], v[24:27]
	v_mfma_f32_16x16x32_bf16 v[16:19], v[144:147], v[208:211], v[16:19]
	v_mfma_f32_16x16x32_bf16 v[8:11], v[158:161], v[208:211], v[8:11]
	v_mfma_f32_16x16x32_bf16 v[60:63], v[154:157], v[188:191], v[60:63]
	v_mfma_f32_16x16x32_bf16 v[56:59], v[162:165], v[188:191], v[56:59]
	v_mfma_f32_16x16x32_bf16 v[48:51], v[154:157], v[196:199], v[48:51]
	v_mfma_f32_16x16x32_bf16 v[40:43], v[162:165], v[196:199], v[40:43]
	v_mfma_f32_16x16x32_bf16 v[32:35], v[154:157], v[204:207], v[32:35]
	v_mfma_f32_16x16x32_bf16 v[24:27], v[162:165], v[204:207], v[24:27]
	v_mfma_f32_16x16x32_bf16 v[16:19], v[154:157], v[212:215], v[16:19]
	v_mfma_f32_16x16x32_bf16 v[8:11], v[162:165], v[212:215], v[8:11]
	v_mfma_f32_16x16x32_bf16 v[52:55], v[166:169], v[182:185], v[52:55]
	v_mfma_f32_16x16x32_bf16 v[44:47], v[174:177], v[182:185], v[44:47]
	v_mfma_f32_16x16x32_bf16 v[36:39], v[166:169], v[192:195], v[36:39]
	v_mfma_f32_16x16x32_bf16 v[28:31], v[174:177], v[192:195], v[28:31]
	v_mfma_f32_16x16x32_bf16 v[20:23], v[166:169], v[200:203], v[20:23]
	v_mfma_f32_16x16x32_bf16 v[12:15], v[174:177], v[200:203], v[12:15]
	v_mfma_f32_16x16x32_bf16 v[4:7], v[166:169], v[208:211], v[4:7]
	v_mfma_f32_16x16x32_bf16 v[0:3], v[174:177], v[208:211], v[0:3]
	v_mfma_f32_16x16x32_bf16 v[52:55], v[170:173], v[188:191], v[52:55]
	v_mfma_f32_16x16x32_bf16 v[44:47], v[178:181], v[188:191], v[44:47]
	v_mfma_f32_16x16x32_bf16 v[36:39], v[170:173], v[196:199], v[36:39]
	v_mfma_f32_16x16x32_bf16 v[28:31], v[178:181], v[196:199], v[28:31]
	v_mfma_f32_16x16x32_bf16 v[20:23], v[170:173], v[204:207], v[20:23]
	v_mfma_f32_16x16x32_bf16 v[12:15], v[178:181], v[204:207], v[12:15]
	v_mfma_f32_16x16x32_bf16 v[4:7], v[170:173], v[212:215], v[4:7]
	v_mfma_f32_16x16x32_bf16 v[0:3], v[178:181], v[212:215], v[0:3]
	s_setprio 0
	s_barrier
	s_add_i32 s51, s51, 2
	s_add_u32 s28, s28, 0x100
	s_addc_u32 s29, s29, 0
	s_add_u32 s49, s49, 0x100
	s_addc_u32 s50, s50, 0
	s_cmpk_gt_u32 s51, 0x7d
	s_cbranch_scc0 .LBB0_803
	s_and_b64 vcc, exec, s[16:17]
	s_cbranch_vccz .LBB0_806
	s_barrier

; #define PG8_STAGE(bufoff, gbase, voff) do { _Pragma("unroll") for (int _i = 0; _i < 2; ++_i) \
;         __builtin_amdgcn_global_load_lds((const unsigned*)((const char*)(gbase) + (voff)[_i]), (PG8_LAS unsigned*)(lds + (bufoff) + ldsw + _i * 8192), 16, 0, 0); } while (0)
; #define PG8_LDA(dst, b, h) do { _Pragma("unroll") for (int m = 0; m < 4; ++m) _Pragma("unroll") for (int k = 0; k < 2; ++k) dst[m][k] = *(const PG8_LAS bf16x8*)(lds + PG8_SA(b, h) + aoff + m * 2048 + k * 1024); } while (0)
; #define PG8_LDB(dst, b, h) do { _Pragma("unroll") for (int n = 0; n < 2; ++n) _Pragma("unroll") for (int k = 0; k < 2; ++k) dst[n][k] = *(const PG8_LAS bf16x8*)(lds + PG8_SB(b, h) + boff + n * 2048 + k * 1024); } while (0)
; #define PG8_MMA(ai, bj, At, Bt) do { __builtin_amdgcn_s_setprio(1); _Pragma("unroll") for (int m = 0; m < 4; ++m) _Pragma("unroll") for (int n = 0; n < 2; ++n) _Pragma("unroll") for (int k = 0; k < 2; ++k) \
;         acc[ai][bj][m][n] = __builtin_amdgcn_mfma_f32_16x16x32_bf16(Bt[n][k], At[m][k], acc[ai][bj][m][n], 0, 0, 0); __builtin_amdgcn_s_setprio(0); } while (0)
; #define PG8_WAIT_V(n) asm volatile("s_waitcnt vmcnt(" #n ")" ::: "memory")
; #define PG8_WAIT_L(n) asm volatile("s_waitcnt lgkmcnt(" #n ")" ::: "memory")
; template <class Epi, class Sched, bool ALIGN_EPI = false, bool SP2 = false>
; __device__ __forceinline__ void gemm_phase(PG8_LAS unsigned char* lds, const Gemm g, const Sched& S, const Epi& E) {
;     ...
;             const bool last = (t == nt - 2);
;             const char* a1 = cA + (size_t)(t + 1) * kstep;
;             const char* a2 = last ? nA : cA + (size_t)(t + 2) * kstep; const char* b2 = last ? nB : cB + (size_t)(t + 2) * kstep;
;             const char* a3 = a2 + kstep; const char* b3 = b2 + kstep;
;             if (last && has_next) S.a_ready(nxt);
;             if constexpr (SP2) {
;             PG8_LDB(B0, 0, 0); PG8_LDB(B1, 0, 1); PG8_SCHED; PG8_LDA(At, 0, 0); PG8_STAGE(PG8_SA(1, 1), a1 + hstep, voffA);
;             PG8_WAIT_V(8); PG8_WAIT_L(0); PG8_BAR; PG8_MMA(0, 0, At, B0); PG8_MMA(0, 1, At, B1); PG8_BAR; PG8_SCHED;
;             PG8_LDA(At, 0, 1); PG8_STAGE(PG8_SB(0, 0), b2, voffB); PG8_STAGE(PG8_SB(0, 1), b2 + hstep, voffB); PG8_STAGE(PG8_SA(0, 0), a2, voffA);
;             PG8_WAIT_V(8); PG8_WAIT_L(0); PG8_BAR; PG8_MMA(1, 0, At, B0); PG8_MMA(1, 1, At, B1); PG8_BAR; PG8_SCHED;
.LBB0_921:
	ds_read_b128 v[144:147], v151
	ds_read_b128 v[156:159], v151 offset:1024
	ds_read_b128 v[160:163], v151 offset:2048
	ds_read_b128 v[164:167], v151 offset:3072
	ds_read_b128 v[168:171], v152
	ds_read_b128 v[172:175], v152 offset:1024
	ds_read_b128 v[176:179], v152 offset:2048
	ds_read_b128 v[180:183], v152 offset:3072
	s_add_u32 s30, s28, 0xfff80080
	s_addc_u32 s31, s29, -1
	s_cmp_eq_u32 s53, 28
	s_cselect_b32 s35, s21, s31
	s_cselect_b32 s34, s49, s30
	s_cselect_b32 s31, s19, s52
	s_cselect_b32 s30, s50, s51
	s_add_i32 m0, s27, 0xc000
	ds_read_b128 v[188:191], v153
	ds_read_b128 v[192:195], v153 offset:1024
	ds_read_b128 v[196:199], v153 offset:2048
	ds_read_b128 v[200:203], v153 offset:3072
	ds_read_b128 v[204:207], v153 offset:4096
	ds_read_b128 v[208:211], v153 offset:5120
	ds_read_b128 v[212:215], v153 offset:6144
	global_load_lds_dwordx4 v136, s[28:29]
	s_add_i32 m0, s27, 0xe000
	ds_read_b128 v[216:219], v153 offset:7168
	global_load_lds_dwordx4 v138, s[28:29]
	s_waitcnt vmcnt(8)
	s_waitcnt lgkmcnt(0)
	s_barrier
	s_setprio 1
	s_waitcnt lgkmcnt(0)
	v_mfma_f32_16x16x32_bf16 v[124:127], v[144:147], v[188:191], v[124:127]
	v_mfma_f32_16x16x32_bf16 v[120:123], v[160:163], v[188:191], v[120:123]
	v_mfma_f32_16x16x32_bf16 v[108:111], v[144:147], v[196:199], v[108:111]
	v_mfma_f32_16x16x32_bf16 v[104:107], v[160:163], v[196:199], v[104:107]
	v_mfma_f32_16x16x32_bf16 v[92:95], v[144:147], v[204:207], v[92:95]
	v_mfma_f32_16x16x32_bf16 v[88:91], v[160:163], v[204:207], v[88:91]
	v_mfma_f32_16x16x32_bf16 v[76:79], v[144:147], v[212:215], v[76:79]
	v_mfma_f32_16x16x32_bf16 v[72:75], v[160:163], v[212:215], v[72:75]
	v_mfma_f32_16x16x32_bf16 v[124:127], v[156:159], v[192:195], v[124:127]
	v_mfma_f32_16x16x32_bf16 v[120:123], v[164:167], v[192:195], v[120:123]
	v_mfma_f32_16x16x32_bf16 v[108:111], v[156:159], v[200:203], v[108:111]
	v_mfma_f32_16x16x32_bf16 v[104:107], v[164:167], v[200:203], v[104:107]
	v_mfma_f32_16x16x32_bf16 v[92:95], v[156:159], v[208:211], v[92:95]
	v_mfma_f32_16x16x32_bf16 v[88:91], v[164:167], v[208:211], v[88:91]
	v_mfma_f32_16x16x32_bf16 v[76:79], v[156:159], v[216:219], v[76:79]
	v_mfma_f32_16x16x32_bf16 v[72:75], v[164:167], v[216:219], v[72:75]
	v_mfma_f32_16x16x32_bf16 v[116:119], v[168:171], v[188:191], v[116:119]
	v_mfma_f32_16x16x32_bf16 v[112:115], v[176:179], v[188:191], v[112:115]
	v_mfma_f32_16x16x32_bf16 v[100:103], v[168:171], v[196:199], v[100:103]
	v_mfma_f32_16x16x32_bf16 v[96:99], v[176:179], v[196:199], v[96:99]
	v_mfma_f32_16x16x32_bf16 v[84:87], v[168:171], v[204:207], v[84:87]
	v_mfma_f32_16x16x32_bf16 v[80:83], v[176:179], v[204:207], v[80:83]
	v_mfma_f32_16x16x32_bf16 v[68:71], v[168:171], v[212:215], v[68:71]
	v_mfma_f32_16x16x32_bf16 v[64:67], v[176:179], v[212:215], v[64:67]
	v_mfma_f32_16x16x32_bf16 v[116:119], v[172:175], v[192:195], v[116:119]
	v_mfma_f32_16x16x32_bf16 v[112:115], v[180:183], v[192:195], v[112:115]
	v_mfma_f32_16x16x32_bf16 v[100:103], v[172:175], v[200:203], v[100:103]
	v_mfma_f32_16x16x32_bf16 v[96:99], v[180:183], v[200:203], v[96:99]
	v_mfma_f32_16x16x32_bf16 v[84:87], v[172:175], v[208:211], v[84:87]
	v_mfma_f32_16x16x32_bf16 v[80:83], v[180:183], v[208:211], v[80:83]
	v_mfma_f32_16x16x32_bf16 v[68:71], v[172:175], v[216:219], v[68:71]
	v_mfma_f32_16x16x32_bf16 v[64:67], v[180:183], v[216:219], v[64:67]
	s_setprio 0
	s_barrier
	s_add_u32 s98, s30, s14
	s_addc_u32 s99, s31, s15
	s_add_u32 s100, s34, s14
	s_addc_u32 s101, s35, s15
	s_add_i32 s54, s45, s1
	s_mov_b32 m0, s54
	ds_read_b128 v[188:191], v153 offset:16384
	ds_read_b128 v[192:195], v153 offset:17408
	ds_read_b128 v[196:199], v153 offset:18432
	ds_read_b128 v[200:203], v153 offset:19456
	global_load_lds_dwordx4 v130, s[30:31]
	s_add_i32 m0, s54, 0x2000
	s_add_u32 s54, s30, 0x80000
	s_addc_u32 s55, s31, 0
	s_add_i32 s56, s46, s1
	global_load_lds_dwordx4 v134, s[30:31]
	s_mov_b32 m0, s56
	ds_read_b128 v[216:219], v153 offset:23552
	global_load_lds_dwordx4 v130, s[54:55]
	s_add_i32 m0, s56, 0x2000
	ds_read_b128 v[212:215], v153 offset:22528
	global_load_lds_dwordx4 v134, s[54:55]
	s_mov_b32 m0, s27
	ds_read_b128 v[208:211], v153 offset:21504
	global_load_lds_dwordx4 v128, s[34:35]
	s_mov_b32 m0, s36
	ds_read_b128 v[204:207], v153 offset:20480
	global_load_lds_dwordx4 v132, s[34:35]
	s_waitcnt vmcnt(8)
	s_waitcnt lgkmcnt(0)
	s_barrier
	s_setprio 1
	s_waitcnt lgkmcnt(0)
	v_mfma_f32_16x16x32_bf16 v[60:63], v[144:147], v[188:191], v[60:63]
	v_mfma_f32_16x16x32_bf16 v[56:59], v[160:163], v[188:191], v[56:59]
	v_mfma_f32_16x16x32_bf16 v[44:47], v[144:147], v[196:199], v[44:47]
	v_mfma_f32_16x16x32_bf16 v[40:43], v[160:163], v[196:199], v[40:43]
	v_mfma_f32_16x16x32_bf16 v[28:31], v[144:147], v[204:207], v[28:31]
	v_mfma_f32_16x16x32_bf16 v[24:27], v[160:163], v[204:207], v[24:27]
	v_mfma_f32_16x16x32_bf16 v[12:15], v[144:147], v[212:215], v[12:15]
	v_mfma_f32_16x16x32_bf16 v[8:11], v[160:163], v[212:215], v[8:11]
	v_mfma_f32_16x16x32_bf16 v[60:63], v[156:159], v[192:195], v[60:63]
	v_mfma_f32_16x16x32_bf16 v[56:59], v[164:167], v[192:195], v[56:59]
	v_mfma_f32_16x16x32_bf16 v[44:47], v[156:159], v[200:203], v[44:47]
	v_mfma_f32_16x16x32_bf16 v[40:43], v[164:167], v[200:203], v[40:43]
	v_mfma_f32_16x16x32_bf16 v[28:31], v[156:159], v[208:211], v[28:31]
	v_mfma_f32_16x16x32_bf16 v[24:27], v[164:167], v[208:211], v[24:27]
	v_mfma_f32_16x16x32_bf16 v[12:15], v[156:159], v[216:219], v[12:15]
	v_mfma_f32_16x16x32_bf16 v[8:11], v[164:167], v[216:219], v[8:11]
	v_mfma_f32_16x16x32_bf16 v[52:55], v[168:171], v[188:191], v[52:55]
	v_mfma_f32_16x16x32_bf16 v[48:51], v[176:179], v[188:191], v[48:51]
	v_mfma_f32_16x16x32_bf16 v[36:39], v[168:171], v[196:199], v[36:39]
	v_mfma_f32_16x16x32_bf16 v[32:35], v[176:179], v[196:199], v[32:35]
	v_mfma_f32_16x16x32_bf16 v[20:23], v[168:171], v[204:207], v[20:23]
	v_mfma_f32_16x16x32_bf16 v[16:19], v[176:179], v[204:207], v[16:19]
	v_mfma_f32_16x16x32_bf16 v[4:7], v[168:171], v[212:215], v[4:7]
	v_mfma_f32_16x16x32_bf16 v[0:3], v[176:179], v[212:215], v[0:3]
	v_mfma_f32_16x16x32_bf16 v[52:55], v[172:175], v[192:195], v[52:55]
	v_mfma_f32_16x16x32_bf16 v[48:51], v[180:183], v[192:195], v[48:51]
	v_mfma_f32_16x16x32_bf16 v[36:39], v[172:175], v[200:203], v[36:39]
	v_mfma_f32_16x16x32_bf16 v[32:35], v[180:183], v[200:203], v[32:35]
	v_mfma_f32_16x16x32_bf16 v[20:23], v[172:175], v[208:211], v[20:23]
	v_mfma_f32_16x16x32_bf16 v[16:19], v[180:183], v[208:211], v[16:19]
	v_mfma_f32_16x16x32_bf16 v[4:7], v[172:175], v[216:219], v[4:7]
	v_mfma_f32_16x16x32_bf16 v[0:3], v[180:183], v[216:219], v[0:3]
	s_setprio 0
	s_barrier
; #define PG8_STAGE(bufoff, gbase, voff) do { _Pragma("unroll") for (int _i = 0; _i < 2; ++_i) \
;         __builtin_amdgcn_global_load_lds((const unsigned*)((const char*)(gbase) + (voff)[_i]), (PG8_LAS unsigned*)(lds + (bufoff) + ldsw + _i * 8192), 16, 0, 0); } while (0)
; #define PG8_LDA(dst, b, h) do { _Pragma("unroll") for (int m = 0; m < 4; ++m) _Pragma("unroll") for (int k = 0; k < 2; ++k) dst[m][k] = *(const PG8_LAS bf16x8*)(lds + PG8_SA(b, h) + aoff + m * 2048 + k * 1024); } while (0)
; #define PG8_LDB(dst, b, h) do { _Pragma("unroll") for (int n = 0; n < 2; ++n) _Pragma("unroll") for (int k = 0; k < 2; ++k) dst[n][k] = *(const PG8_LAS bf16x8*)(lds + PG8_SB(b, h) + boff + n * 2048 + k * 1024); } while (0)
; #define PG8_MMA(ai, bj, At, Bt) do { __builtin_amdgcn_s_setprio(1); _Pragma("unroll") for (int m = 0; m < 4; ++m) _Pragma("unroll") for (int n = 0; n < 2; ++n) _Pragma("unroll") for (int k = 0; k < 2; ++k) \
;         acc[ai][bj][m][n] = __builtin_amdgcn_mfma_f32_16x16x32_bf16(Bt[n][k], At[m][k], acc[ai][bj][m][n], 0, 0, 0); __builtin_amdgcn_s_setprio(0); } while (0)
; #define PG8_WAIT_V(n) asm volatile("s_waitcnt vmcnt(" #n ")" ::: "memory")
; #define PG8_WAIT_L(n) asm volatile("s_waitcnt lgkmcnt(" #n ")" ::: "memory")
; #define PG8_BAR __builtin_amdgcn_s_barrier()
; #define PG8_SCHED __builtin_amdgcn_sched_barrier(0)
; template <class Epi, class Sched, bool ALIGN_EPI = false, bool SP2 = false>
; __device__ __forceinline__ void gemm_phase(PG8_LAS unsigned char* lds, const Gemm g, const Sched& S, const Epi& E) {
;     ...
;             PG8_LDB(B0, 1, 0); PG8_LDB(B1, 1, 1); PG8_SCHED; PG8_LDA(At, 1, 0); PG8_STAGE(PG8_SA(0, 1), a2 + hstep, voffA);
;             PG8_WAIT_V(8); PG8_WAIT_L(0); PG8_BAR; PG8_MMA(0, 0, At, B0); PG8_MMA(0, 1, At, B1); PG8_BAR; PG8_SCHED;
;             PG8_LDA(At, 1, 1); PG8_STAGE(PG8_SB(1, 0), b3, voffB); PG8_STAGE(PG8_SB(1, 1), b3 + hstep, voffB); PG8_STAGE(PG8_SA(1, 0), a3, voffA);
;             PG8_WAIT_V(8); PG8_WAIT_L(0); PG8_BAR; PG8_MMA(1, 0, At, B0); PG8_MMA(1, 1, At, B1); PG8_BAR; PG8_SCHED;
;     ...
;         if constexpr (ALIGN_EPI) { if (wr == 0) PG8_BAR; }
	s_add_i32 s54, 0, 0x18000
	v_add_u32_e32 v155, s54, v150
	s_add_i32 s55, 0, 0x1c000
	ds_read_b128 v[144:147], v155
	ds_read_b128 v[156:159], v155 offset:1024
	ds_read_b128 v[160:163], v155 offset:2048
	ds_read_b128 v[164:167], v155 offset:3072
	v_add_u32_e32 v155, s55, v150
	ds_read_b128 v[168:171], v155
	ds_read_b128 v[172:175], v155 offset:1024
	ds_read_b128 v[176:179], v155 offset:2048
	ds_read_b128 v[180:183], v155 offset:3072
	s_add_u32 s34, s34, 0x80000
	s_addc_u32 s35, s35, 0
	s_mov_b32 m0, s37
	ds_read_b128 v[188:191], v153 offset:32768
	ds_read_b128 v[192:195], v153 offset:33792
	ds_read_b128 v[196:199], v153 offset:34816
	ds_read_b128 v[200:203], v153 offset:35840
	ds_read_b128 v[204:207], v153 offset:36864
	ds_read_b128 v[208:211], v153 offset:37888
	ds_read_b128 v[212:215], v153 offset:38912
	global_load_lds_dwordx4 v128, s[34:35]
	s_mov_b32 m0, s38
	ds_read_b128 v[216:219], v153 offset:39936
	global_load_lds_dwordx4 v132, s[34:35]
	s_waitcnt vmcnt(8)
	s_waitcnt lgkmcnt(0)
	s_barrier
	s_setprio 1
	s_waitcnt lgkmcnt(0)
	v_mfma_f32_16x16x32_bf16 v[124:127], v[144:147], v[188:191], v[124:127]
	v_mfma_f32_16x16x32_bf16 v[120:123], v[160:163], v[188:191], v[120:123]
	v_mfma_f32_16x16x32_bf16 v[108:111], v[144:147], v[196:199], v[108:111]
	v_mfma_f32_16x16x32_bf16 v[104:107], v[160:163], v[196:199], v[104:107]
	v_mfma_f32_16x16x32_bf16 v[92:95], v[144:147], v[204:207], v[92:95]
	v_mfma_f32_16x16x32_bf16 v[88:91], v[160:163], v[204:207], v[88:91]
	v_mfma_f32_16x16x32_bf16 v[76:79], v[144:147], v[212:215], v[76:79]
	v_mfma_f32_16x16x32_bf16 v[72:75], v[160:163], v[212:215], v[72:75]
	v_mfma_f32_16x16x32_bf16 v[124:127], v[156:159], v[192:195], v[124:127]
	v_mfma_f32_16x16x32_bf16 v[120:123], v[164:167], v[192:195], v[120:123]
	v_mfma_f32_16x16x32_bf16 v[108:111], v[156:159], v[200:203], v[108:111]
	v_mfma_f32_16x16x32_bf16 v[104:107], v[164:167], v[200:203], v[104:107]
	v_mfma_f32_16x16x32_bf16 v[92:95], v[156:159], v[208:211], v[92:95]
	v_mfma_f32_16x16x32_bf16 v[88:91], v[164:167], v[208:211], v[88:91]
	v_mfma_f32_16x16x32_bf16 v[76:79], v[156:159], v[216:219], v[76:79]
	v_mfma_f32_16x16x32_bf16 v[72:75], v[164:167], v[216:219], v[72:75]
	v_mfma_f32_16x16x32_bf16 v[116:119], v[168:171], v[188:191], v[116:119]
	v_mfma_f32_16x16x32_bf16 v[112:115], v[176:179], v[188:191], v[112:115]
	v_mfma_f32_16x16x32_bf16 v[100:103], v[168:171], v[196:199], v[100:103]
	v_mfma_f32_16x16x32_bf16 v[96:99], v[176:179], v[196:199], v[96:99]
	v_mfma_f32_16x16x32_bf16 v[84:87], v[168:171], v[204:207], v[84:87]
	v_mfma_f32_16x16x32_bf16 v[80:83], v[176:179], v[204:207], v[80:83]
	v_mfma_f32_16x16x32_bf16 v[68:71], v[168:171], v[212:215], v[68:71]
	v_mfma_f32_16x16x32_bf16 v[64:67], v[176:179], v[212:215], v[64:67]
	v_mfma_f32_16x16x32_bf16 v[116:119], v[172:175], v[192:195], v[116:119]
	v_mfma_f32_16x16x32_bf16 v[112:115], v[180:183], v[192:195], v[112:115]
	v_mfma_f32_16x16x32_bf16 v[100:103], v[172:175], v[200:203], v[100:103]
	v_mfma_f32_16x16x32_bf16 v[96:99], v[180:183], v[200:203], v[96:99]
	v_mfma_f32_16x16x32_bf16 v[84:87], v[172:175], v[208:211], v[84:87]
	v_mfma_f32_16x16x32_bf16 v[80:83], v[180:183], v[208:211], v[80:83]
	v_mfma_f32_16x16x32_bf16 v[68:71], v[172:175], v[216:219], v[68:71]
	v_mfma_f32_16x16x32_bf16 v[64:67], v[180:183], v[216:219], v[64:67]
	s_setprio 0
	s_barrier
	s_add_i32 s34, s54, s1
	s_mov_b32 m0, s34
	ds_read_b128 v[188:191], v153 offset:49152
	ds_read_b128 v[192:195], v153 offset:50176
	ds_read_b128 v[196:199], v153 offset:51200
	ds_read_b128 v[200:203], v153 offset:52224
	global_load_lds_dwordx4 v130, s[98:99]
	s_add_i32 m0, s34, 0x2000
	s_add_u32 s30, s30, 0x80080
	s_addc_u32 s31, s31, 0
	s_add_i32 s34, s55, s1
	global_load_lds_dwordx4 v134, s[98:99]
	s_mov_b32 m0, s34
	ds_read_b128 v[216:219], v153 offset:56320
	global_load_lds_dwordx4 v130, s[30:31]
	s_add_i32 m0, s34, 0x2000
	ds_read_b128 v[212:215], v153 offset:55296
	global_load_lds_dwordx4 v134, s[30:31]
	s_mov_b32 m0, s42
	ds_read_b128 v[208:211], v153 offset:54272
	global_load_lds_dwordx4 v128, s[100:101]
	s_mov_b32 m0, s43
	ds_read_b128 v[204:207], v153 offset:53248
	global_load_lds_dwordx4 v132, s[100:101]
	s_waitcnt vmcnt(8)
	s_waitcnt lgkmcnt(0)
	s_barrier
	s_setprio 1
	s_waitcnt lgkmcnt(0)
	v_mfma_f32_16x16x32_bf16 v[60:63], v[144:147], v[188:191], v[60:63]
	v_mfma_f32_16x16x32_bf16 v[56:59], v[160:163], v[188:191], v[56:59]
	v_mfma_f32_16x16x32_bf16 v[44:47], v[144:147], v[196:199], v[44:47]
	v_mfma_f32_16x16x32_bf16 v[40:43], v[160:163], v[196:199], v[40:43]
	v_mfma_f32_16x16x32_bf16 v[28:31], v[144:147], v[204:207], v[28:31]
	v_mfma_f32_16x16x32_bf16 v[24:27], v[160:163], v[204:207], v[24:27]
	v_mfma_f32_16x16x32_bf16 v[12:15], v[144:147], v[212:215], v[12:15]
	v_mfma_f32_16x16x32_bf16 v[8:11], v[160:163], v[212:215], v[8:11]
	v_mfma_f32_16x16x32_bf16 v[60:63], v[156:159], v[192:195], v[60:63]
	v_mfma_f32_16x16x32_bf16 v[56:59], v[164:167], v[192:195], v[56:59]
	v_mfma_f32_16x16x32_bf16 v[44:47], v[156:159], v[200:203], v[44:47]
	v_mfma_f32_16x16x32_bf16 v[40:43], v[164:167], v[200:203], v[40:43]
	v_mfma_f32_16x16x32_bf16 v[28:31], v[156:159], v[208:211], v[28:31]
	v_mfma_f32_16x16x32_bf16 v[24:27], v[164:167], v[208:211], v[24:27]
	v_mfma_f32_16x16x32_bf16 v[12:15], v[156:159], v[216:219], v[12:15]
	v_mfma_f32_16x16x32_bf16 v[8:11], v[164:167], v[216:219], v[8:11]
	v_mfma_f32_16x16x32_bf16 v[52:55], v[168:171], v[188:191], v[52:55]
	v_mfma_f32_16x16x32_bf16 v[48:51], v[176:179], v[188:191], v[48:51]
	v_mfma_f32_16x16x32_bf16 v[36:39], v[168:171], v[196:199], v[36:39]
	v_mfma_f32_16x16x32_bf16 v[32:35], v[176:179], v[196:199], v[32:35]
	v_mfma_f32_16x16x32_bf16 v[20:23], v[168:171], v[204:207], v[20:23]
	v_mfma_f32_16x16x32_bf16 v[16:19], v[176:179], v[204:207], v[16:19]
	v_mfma_f32_16x16x32_bf16 v[4:7], v[168:171], v[212:215], v[4:7]
	v_mfma_f32_16x16x32_bf16 v[0:3], v[176:179], v[212:215], v[0:3]
	v_mfma_f32_16x16x32_bf16 v[52:55], v[172:175], v[192:195], v[52:55]
	v_mfma_f32_16x16x32_bf16 v[48:51], v[180:183], v[192:195], v[48:51]
	v_mfma_f32_16x16x32_bf16 v[36:39], v[172:175], v[200:203], v[36:39]
	v_mfma_f32_16x16x32_bf16 v[32:35], v[180:183], v[200:203], v[32:35]
	v_mfma_f32_16x16x32_bf16 v[20:23], v[172:175], v[208:211], v[20:23]
	v_mfma_f32_16x16x32_bf16 v[16:19], v[180:183], v[208:211], v[16:19]
	v_mfma_f32_16x16x32_bf16 v[4:7], v[172:175], v[216:219], v[4:7]
	v_mfma_f32_16x16x32_bf16 v[0:3], v[180:183], v[216:219], v[0:3]
	s_setprio 0
	s_barrier
	s_add_i32 s53, s53, 2
	s_add_u32 s28, s28, 0x100
	s_addc_u32 s29, s29, 0
	s_add_u32 s51, s51, 0x100
	s_addc_u32 s52, s52, 0
	s_cmp_gt_u32 s53, 29
	s_cbranch_scc0 .LBB0_921
	s_and_b64 vcc, exec, s[16:17]
	s_cbranch_vccz .LBB0_924
	s_barrier

; #define PG8_STAGE(bufoff, gbase, voff) do { _Pragma("unroll") for (int _i = 0; _i < 2; ++_i) \
;         __builtin_amdgcn_global_load_lds((const unsigned*)((const char*)(gbase) + (voff)[_i]), (PG8_LAS unsigned*)(lds + (bufoff) + ldsw + _i * 8192), 16, 0, 0); } while (0)
; #define PG8_LDA(dst, b, h) do { _Pragma("unroll") for (int m = 0; m < 4; ++m) _Pragma("unroll") for (int k = 0; k < 2; ++k) dst[m][k] = *(const PG8_LAS bf16x8*)(lds + PG8_SA(b, h) + aoff + m * 2048 + k * 1024); } while (0)
; #define PG8_LDB(dst, b, h) do { _Pragma("unroll") for (int n = 0; n < 2; ++n) _Pragma("unroll") for (int k = 0; k < 2; ++k) dst[n][k] = *(const PG8_LAS bf16x8*)(lds + PG8_SB(b, h) + boff + n * 2048 + k * 1024); } while (0)
; #define PG8_MMA(ai, bj, At, Bt) do { __builtin_amdgcn_s_setprio(1); _Pragma("unroll") for (int m = 0; m < 4; ++m) _Pragma("unroll") for (int n = 0; n < 2; ++n) _Pragma("unroll") for (int k = 0; k < 2; ++k) \
;         acc[ai][bj][m][n] = __builtin_amdgcn_mfma_f32_16x16x32_bf16(Bt[n][k], At[m][k], acc[ai][bj][m][n], 0, 0, 0); __builtin_amdgcn_s_setprio(0); } while (0)
; #define PG8_WAIT_V(n) asm volatile("s_waitcnt vmcnt(" #n ")" ::: "memory")
; #define PG8_WAIT_L(n) asm volatile("s_waitcnt lgkmcnt(" #n ")" ::: "memory")
; template <class Epi, class Sched, bool ALIGN_EPI = false, bool SP2 = false>
; __device__ __forceinline__ void gemm_phase(PG8_LAS unsigned char* lds, const Gemm g, const Sched& S, const Epi& E) {
;     ...
;             const bool last = (t == nt - 2);
;             const char* a1 = cA + (size_t)(t + 1) * kstep;
;             const char* a2 = last ? nA : cA + (size_t)(t + 2) * kstep; const char* b2 = last ? nB : cB + (size_t)(t + 2) * kstep;
;             const char* a3 = a2 + kstep; const char* b3 = b2 + kstep;
;             if (last && has_next) S.a_ready(nxt);
;             if constexpr (SP2) {
;             PG8_LDB(B0, 0, 0); PG8_LDB(B1, 0, 1); PG8_SCHED; PG8_LDA(At, 0, 0); PG8_STAGE(PG8_SA(1, 1), a1 + hstep, voffA);
;             PG8_WAIT_V(8); PG8_WAIT_L(0); PG8_BAR; PG8_MMA(0, 0, At, B0); PG8_MMA(0, 1, At, B1); PG8_BAR; PG8_SCHED;
;             PG8_LDA(At, 0, 1); PG8_STAGE(PG8_SB(0, 0), b2, voffB); PG8_STAGE(PG8_SB(0, 1), b2 + hstep, voffB); PG8_STAGE(PG8_SA(0, 0), a2, voffA);
;             PG8_WAIT_V(8); PG8_WAIT_L(0); PG8_BAR; PG8_MMA(1, 0, At, B0); PG8_MMA(1, 1, At, B1); PG8_BAR; PG8_SCHED;
.LBB0_996:
	ds_read_b128 v[144:147], v151
	ds_read_b128 v[154:157], v151 offset:1024
	ds_read_b128 v[158:161], v151 offset:2048
	ds_read_b128 v[162:165], v151 offset:3072
	ds_read_b128 v[166:169], v152
	ds_read_b128 v[170:173], v152 offset:1024
	ds_read_b128 v[174:177], v152 offset:2048
	ds_read_b128 v[178:181], v152 offset:3072
	s_add_u32 s28, s26, 0xffe00080
	s_addc_u32 s29, s27, -1
	s_cmpk_eq_i32 s52, 0x7c
	s_cselect_b32 s31, s19, s29
	s_cselect_b32 s30, s48, s28
	s_cselect_b32 s29, s17, s51
	s_cselect_b32 s28, s49, s50
	s_add_i32 m0, s25, 0xc000
	ds_read_b128 v[182:185], v153
	ds_read_b128 v[186:189], v153 offset:1024
	ds_read_b128 v[190:193], v153 offset:2048
	ds_read_b128 v[194:197], v153 offset:3072
	ds_read_b128 v[198:201], v153 offset:4096
	ds_read_b128 v[202:205], v153 offset:5120
	ds_read_b128 v[206:209], v153 offset:6144
	global_load_lds_dwordx4 v136, s[26:27]
	s_add_i32 m0, s25, 0xe000
	ds_read_b128 v[210:213], v153 offset:7168
	global_load_lds_dwordx4 v138, s[26:27]
	s_waitcnt vmcnt(8)
	s_waitcnt lgkmcnt(0)
	s_barrier
	s_setprio 1
	s_waitcnt lgkmcnt(0)
	v_mfma_f32_16x16x32_bf16 v[124:127], v[144:147], v[182:185], v[124:127]
	v_mfma_f32_16x16x32_bf16 v[120:123], v[158:161], v[182:185], v[120:123]
	v_mfma_f32_16x16x32_bf16 v[112:115], v[144:147], v[190:193], v[112:115]
	v_mfma_f32_16x16x32_bf16 v[104:107], v[158:161], v[190:193], v[104:107]
	v_mfma_f32_16x16x32_bf16 v[96:99], v[144:147], v[198:201], v[96:99]
	v_mfma_f32_16x16x32_bf16 v[88:91], v[158:161], v[198:201], v[88:91]
	v_mfma_f32_16x16x32_bf16 v[80:83], v[144:147], v[206:209], v[80:83]
	v_mfma_f32_16x16x32_bf16 v[72:75], v[158:161], v[206:209], v[72:75]
	v_mfma_f32_16x16x32_bf16 v[124:127], v[154:157], v[186:189], v[124:127]
	v_mfma_f32_16x16x32_bf16 v[120:123], v[162:165], v[186:189], v[120:123]
	v_mfma_f32_16x16x32_bf16 v[112:115], v[154:157], v[194:197], v[112:115]
	v_mfma_f32_16x16x32_bf16 v[104:107], v[162:165], v[194:197], v[104:107]
	v_mfma_f32_16x16x32_bf16 v[96:99], v[154:157], v[202:205], v[96:99]
	v_mfma_f32_16x16x32_bf16 v[88:91], v[162:165], v[202:205], v[88:91]
	v_mfma_f32_16x16x32_bf16 v[80:83], v[154:157], v[210:213], v[80:83]
	v_mfma_f32_16x16x32_bf16 v[72:75], v[162:165], v[210:213], v[72:75]
	v_mfma_f32_16x16x32_bf16 v[116:119], v[166:169], v[182:185], v[116:119]
	v_mfma_f32_16x16x32_bf16 v[108:111], v[174:177], v[182:185], v[108:111]
	v_mfma_f32_16x16x32_bf16 v[100:103], v[166:169], v[190:193], v[100:103]
	v_mfma_f32_16x16x32_bf16 v[92:95], v[174:177], v[190:193], v[92:95]
	v_mfma_f32_16x16x32_bf16 v[84:87], v[166:169], v[198:201], v[84:87]
	v_mfma_f32_16x16x32_bf16 v[76:79], v[174:177], v[198:201], v[76:79]
	v_mfma_f32_16x16x32_bf16 v[68:71], v[166:169], v[206:209], v[68:71]
	v_mfma_f32_16x16x32_bf16 v[64:67], v[174:177], v[206:209], v[64:67]
	v_mfma_f32_16x16x32_bf16 v[116:119], v[170:173], v[186:189], v[116:119]
	v_mfma_f32_16x16x32_bf16 v[108:111], v[178:181], v[186:189], v[108:111]
	v_mfma_f32_16x16x32_bf16 v[100:103], v[170:173], v[194:197], v[100:103]
	v_mfma_f32_16x16x32_bf16 v[92:95], v[178:181], v[194:197], v[92:95]
	v_mfma_f32_16x16x32_bf16 v[84:87], v[170:173], v[202:205], v[84:87]
	v_mfma_f32_16x16x32_bf16 v[76:79], v[178:181], v[202:205], v[76:79]
	v_mfma_f32_16x16x32_bf16 v[68:71], v[170:173], v[210:213], v[68:71]
	v_mfma_f32_16x16x32_bf16 v[64:67], v[178:181], v[210:213], v[64:67]
	s_setprio 0
	s_barrier
	s_add_u32 s98, s28, s12
	s_addc_u32 s99, s29, s13
	s_add_u32 s100, s30, s12
	s_addc_u32 s101, s31, s13
	s_add_i32 s53, s44, s36
	s_mov_b32 m0, s53
	ds_read_b128 v[182:185], v153 offset:16384
	ds_read_b128 v[186:189], v153 offset:17408
	ds_read_b128 v[190:193], v153 offset:18432
	ds_read_b128 v[194:197], v153 offset:19456
	global_load_lds_dwordx4 v130, s[28:29]
	s_add_i32 m0, s53, 0x2000
	s_add_u32 s54, s28, 0x200000
	s_addc_u32 s55, s29, 0
	s_add_i32 s53, s45, s36
	global_load_lds_dwordx4 v134, s[28:29]
	s_mov_b32 m0, s53
	ds_read_b128 v[210:213], v153 offset:23552
	global_load_lds_dwordx4 v130, s[54:55]
	s_add_i32 m0, s53, 0x2000
	ds_read_b128 v[206:209], v153 offset:22528
	global_load_lds_dwordx4 v134, s[54:55]
	s_mov_b32 m0, s25
	ds_read_b128 v[202:205], v153 offset:21504
	global_load_lds_dwordx4 v128, s[30:31]
	s_mov_b32 m0, s37
	ds_read_b128 v[198:201], v153 offset:20480
	global_load_lds_dwordx4 v132, s[30:31]
	s_waitcnt vmcnt(8)
	s_waitcnt lgkmcnt(0)
	s_barrier
	s_setprio 1
	s_waitcnt lgkmcnt(0)
	v_mfma_f32_16x16x32_bf16 v[60:63], v[144:147], v[182:185], v[60:63]
	v_mfma_f32_16x16x32_bf16 v[56:59], v[158:161], v[182:185], v[56:59]
	v_mfma_f32_16x16x32_bf16 v[48:51], v[144:147], v[190:193], v[48:51]
	v_mfma_f32_16x16x32_bf16 v[40:43], v[158:161], v[190:193], v[40:43]
	v_mfma_f32_16x16x32_bf16 v[32:35], v[144:147], v[198:201], v[32:35]
	v_mfma_f32_16x16x32_bf16 v[24:27], v[158:161], v[198:201], v[24:27]
	v_mfma_f32_16x16x32_bf16 v[16:19], v[144:147], v[206:209], v[16:19]
	v_mfma_f32_16x16x32_bf16 v[8:11], v[158:161], v[206:209], v[8:11]
	v_mfma_f32_16x16x32_bf16 v[60:63], v[154:157], v[186:189], v[60:63]
	v_mfma_f32_16x16x32_bf16 v[56:59], v[162:165], v[186:189], v[56:59]
	v_mfma_f32_16x16x32_bf16 v[48:51], v[154:157], v[194:197], v[48:51]
	v_mfma_f32_16x16x32_bf16 v[40:43], v[162:165], v[194:197], v[40:43]
	v_mfma_f32_16x16x32_bf16 v[32:35], v[154:157], v[202:205], v[32:35]
	v_mfma_f32_16x16x32_bf16 v[24:27], v[162:165], v[202:205], v[24:27]
	v_mfma_f32_16x16x32_bf16 v[16:19], v[154:157], v[210:213], v[16:19]
	v_mfma_f32_16x16x32_bf16 v[8:11], v[162:165], v[210:213], v[8:11]
	v_mfma_f32_16x16x32_bf16 v[52:55], v[166:169], v[182:185], v[52:55]
	v_mfma_f32_16x16x32_bf16 v[44:47], v[174:177], v[182:185], v[44:47]
	v_mfma_f32_16x16x32_bf16 v[36:39], v[166:169], v[190:193], v[36:39]
	v_mfma_f32_16x16x32_bf16 v[28:31], v[174:177], v[190:193], v[28:31]
	v_mfma_f32_16x16x32_bf16 v[20:23], v[166:169], v[198:201], v[20:23]
	v_mfma_f32_16x16x32_bf16 v[12:15], v[174:177], v[198:201], v[12:15]
	v_mfma_f32_16x16x32_bf16 v[4:7], v[166:169], v[206:209], v[4:7]
	v_mfma_f32_16x16x32_bf16 v[0:3], v[174:177], v[206:209], v[0:3]
	v_mfma_f32_16x16x32_bf16 v[52:55], v[170:173], v[186:189], v[52:55]
	v_mfma_f32_16x16x32_bf16 v[44:47], v[178:181], v[186:189], v[44:47]
	v_mfma_f32_16x16x32_bf16 v[36:39], v[170:173], v[194:197], v[36:39]
	v_mfma_f32_16x16x32_bf16 v[28:31], v[178:181], v[194:197], v[28:31]
	v_mfma_f32_16x16x32_bf16 v[20:23], v[170:173], v[202:205], v[20:23]
	v_mfma_f32_16x16x32_bf16 v[12:15], v[178:181], v[202:205], v[12:15]
	v_mfma_f32_16x16x32_bf16 v[4:7], v[170:173], v[210:213], v[4:7]
	v_mfma_f32_16x16x32_bf16 v[0:3], v[178:181], v[210:213], v[0:3]
	s_setprio 0
	s_barrier
; #define PG8_STAGE(bufoff, gbase, voff) do { _Pragma("unroll") for (int _i = 0; _i < 2; ++_i) \
;         __builtin_amdgcn_global_load_lds((const unsigned*)((const char*)(gbase) + (voff)[_i]), (PG8_LAS unsigned*)(lds + (bufoff) + ldsw + _i * 8192), 16, 0, 0); } while (0)
; #define PG8_LDA(dst, b, h) do { _Pragma("unroll") for (int m = 0; m < 4; ++m) _Pragma("unroll") for (int k = 0; k < 2; ++k) dst[m][k] = *(const PG8_LAS bf16x8*)(lds + PG8_SA(b, h) + aoff + m * 2048 + k * 1024); } while (0)
; #define PG8_LDB(dst, b, h) do { _Pragma("unroll") for (int n = 0; n < 2; ++n) _Pragma("unroll") for (int k = 0; k < 2; ++k) dst[n][k] = *(const PG8_LAS bf16x8*)(lds + PG8_SB(b, h) + boff + n * 2048 + k * 1024); } while (0)
; #define PG8_MMA(ai, bj, At, Bt) do { __builtin_amdgcn_s_setprio(1); _Pragma("unroll") for (int m = 0; m < 4; ++m) _Pragma("unroll") for (int n = 0; n < 2; ++n) _Pragma("unroll") for (int k = 0; k < 2; ++k) \
;         acc[ai][bj][m][n] = __builtin_amdgcn_mfma_f32_16x16x32_bf16(Bt[n][k], At[m][k], acc[ai][bj][m][n], 0, 0, 0); __builtin_amdgcn_s_setprio(0); } while (0)
; #define PG8_WAIT_V(n) asm volatile("s_waitcnt vmcnt(" #n ")" ::: "memory")
; #define PG8_WAIT_L(n) asm volatile("s_waitcnt lgkmcnt(" #n ")" ::: "memory")
; #define PG8_BAR __builtin_amdgcn_s_barrier()
; #define PG8_SCHED __builtin_amdgcn_sched_barrier(0)
; template <class Epi, class Sched, bool ALIGN_EPI = false, bool SP2 = false>
; __device__ __forceinline__ void gemm_phase(PG8_LAS unsigned char* lds, const Gemm g, const Sched& S, const Epi& E) {
;     ...
;             PG8_LDB(B0, 1, 0); PG8_LDB(B1, 1, 1); PG8_SCHED; PG8_LDA(At, 1, 0); PG8_STAGE(PG8_SA(0, 1), a2 + hstep, voffA);
;             PG8_WAIT_V(8); PG8_WAIT_L(0); PG8_BAR; PG8_MMA(0, 0, At, B0); PG8_MMA(0, 1, At, B1); PG8_BAR; PG8_SCHED;
;             PG8_LDA(At, 1, 1); PG8_STAGE(PG8_SB(1, 0), b3, voffB); PG8_STAGE(PG8_SB(1, 1), b3 + hstep, voffB); PG8_STAGE(PG8_SA(1, 0), a3, voffA);
;             PG8_WAIT_V(8); PG8_WAIT_L(0); PG8_BAR; PG8_MMA(1, 0, At, B0); PG8_MMA(1, 1, At, B1); PG8_BAR; PG8_SCHED;
;     ...
;         if constexpr (ALIGN_EPI) { if (wr == 0) PG8_BAR; }
	s_add_i32 s53, 0, 0x18000
	s_add_i32 s54, 0, 0x1c000
	v_add_u32_e32 v162, s53, v150
	v_add_u32_e32 v178, s54, v150
	ds_read_b128 v[144:147], v162
	ds_read_b128 v[154:157], v162 offset:1024
	ds_read_b128 v[158:161], v162 offset:2048
	ds_read_b128 v[162:165], v162 offset:3072
	ds_read_b128 v[166:169], v178
	ds_read_b128 v[170:173], v178 offset:1024
	ds_read_b128 v[174:177], v178 offset:2048
	ds_read_b128 v[178:181], v178 offset:3072
	s_add_u32 s30, s30, 0x200000
	s_addc_u32 s31, s31, 0
	s_mov_b32 m0, s38
	ds_read_b128 v[182:185], v153 offset:32768
	ds_read_b128 v[186:189], v153 offset:33792
	ds_read_b128 v[190:193], v153 offset:34816
	ds_read_b128 v[194:197], v153 offset:35840
	ds_read_b128 v[198:201], v153 offset:36864
	ds_read_b128 v[202:205], v153 offset:37888
	ds_read_b128 v[206:209], v153 offset:38912
	global_load_lds_dwordx4 v128, s[30:31]
	s_mov_b32 m0, s39
	ds_read_b128 v[210:213], v153 offset:39936
	global_load_lds_dwordx4 v132, s[30:31]
	s_waitcnt vmcnt(8)
	s_waitcnt lgkmcnt(0)
	s_barrier
	s_setprio 1
	s_waitcnt lgkmcnt(0)
	v_mfma_f32_16x16x32_bf16 v[124:127], v[144:147], v[182:185], v[124:127]
	v_mfma_f32_16x16x32_bf16 v[120:123], v[158:161], v[182:185], v[120:123]
	v_mfma_f32_16x16x32_bf16 v[112:115], v[144:147], v[190:193], v[112:115]
	v_mfma_f32_16x16x32_bf16 v[104:107], v[158:161], v[190:193], v[104:107]
	v_mfma_f32_16x16x32_bf16 v[96:99], v[144:147], v[198:201], v[96:99]
	v_mfma_f32_16x16x32_bf16 v[88:91], v[158:161], v[198:201], v[88:91]
	v_mfma_f32_16x16x32_bf16 v[80:83], v[144:147], v[206:209], v[80:83]
	v_mfma_f32_16x16x32_bf16 v[72:75], v[158:161], v[206:209], v[72:75]
	v_mfma_f32_16x16x32_bf16 v[124:127], v[154:157], v[186:189], v[124:127]
	v_mfma_f32_16x16x32_bf16 v[120:123], v[162:165], v[186:189], v[120:123]
	v_mfma_f32_16x16x32_bf16 v[112:115], v[154:157], v[194:197], v[112:115]
	v_mfma_f32_16x16x32_bf16 v[104:107], v[162:165], v[194:197], v[104:107]
	v_mfma_f32_16x16x32_bf16 v[96:99], v[154:157], v[202:205], v[96:99]
	v_mfma_f32_16x16x32_bf16 v[88:91], v[162:165], v[202:205], v[88:91]
	v_mfma_f32_16x16x32_bf16 v[80:83], v[154:157], v[210:213], v[80:83]
	v_mfma_f32_16x16x32_bf16 v[72:75], v[162:165], v[210:213], v[72:75]
	v_mfma_f32_16x16x32_bf16 v[116:119], v[166:169], v[182:185], v[116:119]
	v_mfma_f32_16x16x32_bf16 v[108:111], v[174:177], v[182:185], v[108:111]
	v_mfma_f32_16x16x32_bf16 v[100:103], v[166:169], v[190:193], v[100:103]
	v_mfma_f32_16x16x32_bf16 v[92:95], v[174:177], v[190:193], v[92:95]
	v_mfma_f32_16x16x32_bf16 v[84:87], v[166:169], v[198:201], v[84:87]
	v_mfma_f32_16x16x32_bf16 v[76:79], v[174:177], v[198:201], v[76:79]
	v_mfma_f32_16x16x32_bf16 v[68:71], v[166:169], v[206:209], v[68:71]
	v_mfma_f32_16x16x32_bf16 v[64:67], v[174:177], v[206:209], v[64:67]
	v_mfma_f32_16x16x32_bf16 v[116:119], v[170:173], v[186:189], v[116:119]
	v_mfma_f32_16x16x32_bf16 v[108:111], v[178:181], v[186:189], v[108:111]
	v_mfma_f32_16x16x32_bf16 v[100:103], v[170:173], v[194:197], v[100:103]
	v_mfma_f32_16x16x32_bf16 v[92:95], v[178:181], v[194:197], v[92:95]
	v_mfma_f32_16x16x32_bf16 v[84:87], v[170:173], v[202:205], v[84:87]
	v_mfma_f32_16x16x32_bf16 v[76:79], v[178:181], v[202:205], v[76:79]
	v_mfma_f32_16x16x32_bf16 v[68:71], v[170:173], v[210:213], v[68:71]
	v_mfma_f32_16x16x32_bf16 v[64:67], v[178:181], v[210:213], v[64:67]
	s_setprio 0
	s_barrier
	s_add_i32 s30, s53, s36
	s_mov_b32 m0, s30
	ds_read_b128 v[182:185], v153 offset:49152
	ds_read_b128 v[186:189], v153 offset:50176
	ds_read_b128 v[190:193], v153 offset:51200
	ds_read_b128 v[194:197], v153 offset:52224
	global_load_lds_dwordx4 v130, s[98:99]
	s_add_i32 m0, s30, 0x2000
	s_add_u32 s28, s28, 0x200080
	s_addc_u32 s29, s29, 0
	s_add_i32 s30, s54, s36
	global_load_lds_dwordx4 v134, s[98:99]
	s_mov_b32 m0, s30
	ds_read_b128 v[210:213], v153 offset:56320
	global_load_lds_dwordx4 v130, s[28:29]
	s_add_i32 m0, s30, 0x2000
	ds_read_b128 v[206:209], v153 offset:55296
	global_load_lds_dwordx4 v134, s[28:29]
	s_mov_b32 m0, s41
	ds_read_b128 v[202:205], v153 offset:54272
	global_load_lds_dwordx4 v128, s[100:101]
	s_mov_b32 m0, s42
	ds_read_b128 v[198:201], v153 offset:53248
	global_load_lds_dwordx4 v132, s[100:101]
	s_waitcnt vmcnt(8)
	s_waitcnt lgkmcnt(0)
	s_barrier
	s_setprio 1
	s_waitcnt lgkmcnt(0)
	v_mfma_f32_16x16x32_bf16 v[60:63], v[144:147], v[182:185], v[60:63]
	v_mfma_f32_16x16x32_bf16 v[56:59], v[158:161], v[182:185], v[56:59]
	v_mfma_f32_16x16x32_bf16 v[48:51], v[144:147], v[190:193], v[48:51]
	v_mfma_f32_16x16x32_bf16 v[40:43], v[158:161], v[190:193], v[40:43]
	v_mfma_f32_16x16x32_bf16 v[32:35], v[144:147], v[198:201], v[32:35]
	v_mfma_f32_16x16x32_bf16 v[24:27], v[158:161], v[198:201], v[24:27]
	v_mfma_f32_16x16x32_bf16 v[16:19], v[144:147], v[206:209], v[16:19]
	v_mfma_f32_16x16x32_bf16 v[8:11], v[158:161], v[206:209], v[8:11]
	v_mfma_f32_16x16x32_bf16 v[60:63], v[154:157], v[186:189], v[60:63]
	v_mfma_f32_16x16x32_bf16 v[56:59], v[162:165], v[186:189], v[56:59]
	v_mfma_f32_16x16x32_bf16 v[48:51], v[154:157], v[194:197], v[48:51]
	v_mfma_f32_16x16x32_bf16 v[40:43], v[162:165], v[194:197], v[40:43]
	v_mfma_f32_16x16x32_bf16 v[32:35], v[154:157], v[202:205], v[32:35]
	v_mfma_f32_16x16x32_bf16 v[24:27], v[162:165], v[202:205], v[24:27]
	v_mfma_f32_16x16x32_bf16 v[16:19], v[154:157], v[210:213], v[16:19]
	v_mfma_f32_16x16x32_bf16 v[8:11], v[162:165], v[210:213], v[8:11]
	v_mfma_f32_16x16x32_bf16 v[52:55], v[166:169], v[182:185], v[52:55]
	v_mfma_f32_16x16x32_bf16 v[44:47], v[174:177], v[182:185], v[44:47]
	v_mfma_f32_16x16x32_bf16 v[36:39], v[166:169], v[190:193], v[36:39]
	v_mfma_f32_16x16x32_bf16 v[28:31], v[174:177], v[190:193], v[28:31]
	v_mfma_f32_16x16x32_bf16 v[20:23], v[166:169], v[198:201], v[20:23]
	v_mfma_f32_16x16x32_bf16 v[12:15], v[174:177], v[198:201], v[12:15]
	v_mfma_f32_16x16x32_bf16 v[4:7], v[166:169], v[206:209], v[4:7]
	v_mfma_f32_16x16x32_bf16 v[0:3], v[174:177], v[206:209], v[0:3]
	v_mfma_f32_16x16x32_bf16 v[52:55], v[170:173], v[186:189], v[52:55]
	v_mfma_f32_16x16x32_bf16 v[44:47], v[178:181], v[186:189], v[44:47]
	v_mfma_f32_16x16x32_bf16 v[36:39], v[170:173], v[194:197], v[36:39]
	v_mfma_f32_16x16x32_bf16 v[28:31], v[178:181], v[194:197], v[28:31]
	v_mfma_f32_16x16x32_bf16 v[20:23], v[170:173], v[202:205], v[20:23]
	v_mfma_f32_16x16x32_bf16 v[12:15], v[178:181], v[202:205], v[12:15]
	v_mfma_f32_16x16x32_bf16 v[4:7], v[170:173], v[210:213], v[4:7]
	v_mfma_f32_16x16x32_bf16 v[0:3], v[178:181], v[210:213], v[0:3]
	s_setprio 0
	s_barrier
	s_add_i32 s52, s52, 2
	s_add_u32 s26, s26, 0x100
	s_addc_u32 s27, s27, 0
	s_add_u32 s50, s50, 0x100
	s_addc_u32 s51, s51, 0
	s_cmpk_gt_u32 s52, 0x7d
	s_cbranch_scc0 .LBB0_996
	s_and_b64 vcc, exec, s[14:15]
	s_cbranch_vccz .LBB0_999
	s_barrier
